# v044 + GEMM loop back-edge pointer updates hoisted in front of the closing barrier (3 loops) + vmcnt(8)/lgkmcnt(0) merged into one s_waitcnt (24 sites)
# baseline (speedup 1.0000x reference)
; #define PG8_STAGE(bufoff, gbase, voff) do { _Pragma("unroll") for (int _i = 0; _i < 2; ++_i) \
;         __builtin_amdgcn_global_load_lds((const unsigned*)((const char*)(gbase) + (voff)[_i]), (LAS unsigned*)(lds + (bufoff) + ldsw + _i * 8192), 16, 0, 0); } while (0)
; #define PG8_LDA(dst, b, h) do { _Pragma("unroll") for (int m = 0; m < 4; ++m) _Pragma("unroll") for (int k = 0; k < 2; ++k) dst[m][k] = *(const LAS bf16x8*)(lds + PG8_SA(b, h) + aoff + m * 2048 + k * 1024); } while (0)
; #define PG8_LDB(dst, b, h) do { _Pragma("unroll") for (int n = 0; n < 2; ++n) _Pragma("unroll") for (int k = 0; k < 2; ++k) dst[n][k] = *(const LAS bf16x8*)(lds + PG8_SB(b, h) + boff + n * 2048 + k * 1024); } while (0)
; #define PG8_MMA(ai, bj, At, Bt) do { __builtin_amdgcn_s_setprio(1); _Pragma("unroll") for (int m = 0; m < 4; ++m) _Pragma("unroll") for (int n = 0; n < 2; ++n) _Pragma("unroll") for (int k = 0; k < 2; ++k) \
;         acc[ai][bj][m][n] = __builtin_amdgcn_mfma_f32_16x16x32_bf16(Bt[n][k], At[m][k], acc[ai][bj][m][n], 0, 0, 0); __builtin_amdgcn_s_setprio(0); } while (0)
; #define PG8_WAIT_V(n) asm volatile("s_waitcnt vmcnt(" #n ")" ::: "memory")
; #define PG8_WAIT_L(n) asm volatile("s_waitcnt lgkmcnt(" #n ")" ::: "memory")
; template <class Epi, class Sched, bool ALIGN_EPI = false, bool SP2 = false>
; __device__ __forceinline__ void gemm_phase(LAS unsigned char* lds, const Gemm g, const Sched& S, const Epi& E) {
;     ...
;         for (int t = 0; t < nt; t += 2) {
;             const bool last = (t == nt - 2);
;             const char* a1 = cA + (size_t)(t + 1) * kstep;
;             const char* a2 = last ? nA : cA + (size_t)(t + 2) * kstep; const char* b2 = last ? nB : cB + (size_t)(t + 2) * kstep;
;             const char* a3 = a2 + kstep; const char* b3 = b2 + kstep;
;             if (last && has_next) S.a_ready(nxt);
;             if constexpr (SP2) {
;             PG8_LDB(B0, 0, 0); PG8_LDB(B1, 0, 1); PG8_SCHED; PG8_LDA(At, 0, 0); PG8_STAGE(PG8_SA(1, 1), a1 + hstepA, voffA);
;             PG8_WAIT_V(8); PG8_WAIT_L(0); PG8_BAR; PG8_MMA(0, 0, At, B0); PG8_MMA(0, 1, At, B1); PG8_BAR; PG8_SCHED;
;             PG8_LDA(At, 0, 1); PG8_STAGE(PG8_SB(0, 0), b2, voffB); PG8_STAGE(PG8_SB(0, 1), b2 + hstepB, voffB); PG8_STAGE(PG8_SA(0, 0), a2, voffA);
;             PG8_WAIT_V(8); PG8_WAIT_L(0); PG8_BAR; PG8_MMA(1, 0, At, B0); PG8_MMA(1, 1, At, B1); PG8_BAR; PG8_SCHED;
.LBB0_349:
	ds_read_b128 v[156:159], v149
	ds_read_b128 v[160:163], v149 offset:1024
	ds_read_b128 v[164:167], v149 offset:2048
	ds_read_b128 v[168:171], v149 offset:3072
	ds_read_b128 v[172:175], v150
	ds_read_b128 v[176:179], v150 offset:1024
	ds_read_b128 v[180:183], v150 offset:2048
	ds_read_b128 v[184:187], v150 offset:3072
	s_add_u32 s24, s22, 0xfff80080
	s_addc_u32 s25, s23, -1
	s_cmp_eq_u32 s58, 28
	s_cselect_b32 s27, s15, s25
	s_cselect_b32 s26, s47, s24
	s_cselect_b32 s25, s13, s55
	s_cselect_b32 s24, s50, s51
	v_lshl_add_u64 v[146:147], s[22:23], 0, v[138:139]
	s_add_i32 m0, s21, 0xc000
	ds_read_b128 v[188:191], v151
	ds_read_b128 v[192:195], v151 offset:1024
	ds_read_b128 v[196:199], v151 offset:2048
	ds_read_b128 v[200:203], v151 offset:3072
	ds_read_b128 v[204:207], v151 offset:4096
	ds_read_b128 v[208:211], v151 offset:5120
	ds_read_b128 v[212:215], v151 offset:6144
	ds_read_b128 v[216:219], v151 offset:7168
	global_load_lds_dwordx4 v[146:147], off
	v_lshl_add_u64 v[146:147], s[22:23], 0, v[140:141]
	s_add_i32 m0, s21, 0xe000
	s_nop 0
	global_load_lds_dwordx4 v[146:147], off
	s_waitcnt vmcnt(8) lgkmcnt(0)
	s_setprio 1
	s_barrier
	v_mfma_f32_16x16x32_bf16 v[126:129], v[156:159], v[188:191], v[126:129]
	v_mfma_f32_16x16x32_bf16 v[122:125], v[164:167], v[188:191], v[122:125]
	v_mfma_f32_16x16x32_bf16 v[118:121], v[156:159], v[196:199], v[118:121]
	v_mfma_f32_16x16x32_bf16 v[110:113], v[164:167], v[196:199], v[110:113]
	v_mfma_f32_16x16x32_bf16 v[102:105], v[156:159], v[204:207], v[102:105]
	v_mfma_f32_16x16x32_bf16 v[94:97], v[164:167], v[204:207], v[94:97]
	v_mfma_f32_16x16x32_bf16 v[86:89], v[156:159], v[212:215], v[86:89]
	v_mfma_f32_16x16x32_bf16 v[78:81], v[164:167], v[212:215], v[78:81]
	v_mfma_f32_16x16x32_bf16 v[126:129], v[160:163], v[192:195], v[126:129]
	v_mfma_f32_16x16x32_bf16 v[122:125], v[168:171], v[192:195], v[122:125]
	v_mfma_f32_16x16x32_bf16 v[118:121], v[160:163], v[200:203], v[118:121]
	v_mfma_f32_16x16x32_bf16 v[110:113], v[168:171], v[200:203], v[110:113]
	v_mfma_f32_16x16x32_bf16 v[102:105], v[160:163], v[208:211], v[102:105]
	v_mfma_f32_16x16x32_bf16 v[94:97], v[168:171], v[208:211], v[94:97]
	v_mfma_f32_16x16x32_bf16 v[86:89], v[160:163], v[216:219], v[86:89]
	v_mfma_f32_16x16x32_bf16 v[78:81], v[168:171], v[216:219], v[78:81]
	s_setprio 0
	s_setprio 1
	v_mfma_f32_16x16x32_bf16 v[114:117], v[172:175], v[188:191], v[114:117]
	v_mfma_f32_16x16x32_bf16 v[106:109], v[180:183], v[188:191], v[106:109]
	v_mfma_f32_16x16x32_bf16 v[98:101], v[172:175], v[196:199], v[98:101]
	v_mfma_f32_16x16x32_bf16 v[90:93], v[180:183], v[196:199], v[90:93]
	v_mfma_f32_16x16x32_bf16 v[82:85], v[172:175], v[204:207], v[82:85]
	v_mfma_f32_16x16x32_bf16 v[74:77], v[180:183], v[204:207], v[74:77]
	v_mfma_f32_16x16x32_bf16 v[70:73], v[172:175], v[212:215], v[70:73]
	v_mfma_f32_16x16x32_bf16 v[66:69], v[180:183], v[212:215], v[66:69]
	v_mfma_f32_16x16x32_bf16 v[114:117], v[176:179], v[192:195], v[114:117]
	v_mfma_f32_16x16x32_bf16 v[106:109], v[184:187], v[192:195], v[106:109]
	v_mfma_f32_16x16x32_bf16 v[98:101], v[176:179], v[200:203], v[98:101]
	v_mfma_f32_16x16x32_bf16 v[90:93], v[184:187], v[200:203], v[90:93]
	v_mfma_f32_16x16x32_bf16 v[82:85], v[176:179], v[208:211], v[82:85]
	v_mfma_f32_16x16x32_bf16 v[74:77], v[184:187], v[208:211], v[74:77]
	v_mfma_f32_16x16x32_bf16 v[70:73], v[176:179], v[216:219], v[70:73]
	v_mfma_f32_16x16x32_bf16 v[66:69], v[184:187], v[216:219], v[66:69]
	s_setprio 0
	s_barrier
	s_add_i32 s59, s40, s28
	v_lshl_add_u64 v[146:147], s[24:25], 0, v[134:135]
	s_mov_b32 m0, s59
	ds_read_b128 v[188:191], v151 offset:16384
	ds_read_b128 v[192:195], v151 offset:17408
	ds_read_b128 v[196:199], v151 offset:18432
	ds_read_b128 v[200:203], v151 offset:19456
	ds_read_b128 v[204:207], v151 offset:20480
	ds_read_b128 v[208:211], v151 offset:21504
	ds_read_b128 v[212:215], v151 offset:22528
	ds_read_b128 v[216:219], v151 offset:23552
	global_load_lds_dwordx4 v[146:147], off
	s_add_i32 m0, s59, 0x2000
	s_add_u32 s60, s24, 0x80000
	v_lshl_add_u64 v[220:221], s[24:25], 0, v[130:131]
	s_addc_u32 s61, s25, 0
	s_add_i32 s59, s41, s28
	global_load_lds_dwordx4 v[220:221], off
	v_lshl_add_u64 v[222:223], s[60:61], 0, v[134:135]
	s_mov_b32 m0, s59
	v_lshl_add_u64 v[224:225], s[26:27], 0, v[132:133]
	global_load_lds_dwordx4 v[222:223], off
	v_lshl_add_u64 v[222:223], s[60:61], 0, v[130:131]
	s_add_i32 m0, s59, 0x2000
	s_nop 0
	global_load_lds_dwordx4 v[222:223], off
	v_lshl_add_u64 v[222:223], s[26:27], 0, v[136:137]
	s_mov_b32 m0, s21
	s_nop 0
	global_load_lds_dwordx4 v[222:223], off
	s_mov_b32 m0, s31
	s_nop 0
	global_load_lds_dwordx4 v[224:225], off
	s_waitcnt vmcnt(8) lgkmcnt(0)
	s_setprio 1
	s_barrier
; #define PG8_STAGE(bufoff, gbase, voff) do { _Pragma("unroll") for (int _i = 0; _i < 2; ++_i) \
;         __builtin_amdgcn_global_load_lds((const unsigned*)((const char*)(gbase) + (voff)[_i]), (LAS unsigned*)(lds + (bufoff) + ldsw + _i * 8192), 16, 0, 0); } while (0)
; #define PG8_LDA(dst, b, h) do { _Pragma("unroll") for (int m = 0; m < 4; ++m) _Pragma("unroll") for (int k = 0; k < 2; ++k) dst[m][k] = *(const LAS bf16x8*)(lds + PG8_SA(b, h) + aoff + m * 2048 + k * 1024); } while (0)
; #define PG8_LDB(dst, b, h) do { _Pragma("unroll") for (int n = 0; n < 2; ++n) _Pragma("unroll") for (int k = 0; k < 2; ++k) dst[n][k] = *(const LAS bf16x8*)(lds + PG8_SB(b, h) + boff + n * 2048 + k * 1024); } while (0)
; #define PG8_MMA(ai, bj, At, Bt) do { __builtin_amdgcn_s_setprio(1); _Pragma("unroll") for (int m = 0; m < 4; ++m) _Pragma("unroll") for (int n = 0; n < 2; ++n) _Pragma("unroll") for (int k = 0; k < 2; ++k) \
;         acc[ai][bj][m][n] = __builtin_amdgcn_mfma_f32_16x16x32_bf16(Bt[n][k], At[m][k], acc[ai][bj][m][n], 0, 0, 0); __builtin_amdgcn_s_setprio(0); } while (0)
; #define PG8_WAIT_V(n) asm volatile("s_waitcnt vmcnt(" #n ")" ::: "memory")
; #define PG8_WAIT_L(n) asm volatile("s_waitcnt lgkmcnt(" #n ")" ::: "memory")
; #define PG8_BAR __builtin_amdgcn_s_barrier()
; #define PG8_SCHED __builtin_amdgcn_sched_barrier(0)
; template <class Epi, class Sched, bool ALIGN_EPI = false, bool SP2 = false>
; __device__ __forceinline__ void gemm_phase(LAS unsigned char* lds, const Gemm g, const Sched& S, const Epi& E) {
;     ...
;             PG8_WAIT_V(8); PG8_WAIT_L(0); PG8_BAR; PG8_MMA(1, 0, At, B0); PG8_MMA(1, 1, At, B1); PG8_BAR; PG8_SCHED;
;             PG8_LDB(B0, 1, 0); PG8_LDB(B1, 1, 1); PG8_SCHED; PG8_LDA(At, 1, 0); PG8_STAGE(PG8_SA(0, 1), a2 + hstepA, voffA);
;             PG8_WAIT_V(8); PG8_WAIT_L(0); PG8_BAR; PG8_MMA(0, 0, At, B0); PG8_MMA(0, 1, At, B1); PG8_BAR; PG8_SCHED;
	v_mfma_f32_16x16x32_bf16 v[62:65], v[156:159], v[188:191], v[62:65]
	v_mfma_f32_16x16x32_bf16 v[58:61], v[164:167], v[188:191], v[58:61]
	v_mfma_f32_16x16x32_bf16 v[54:57], v[156:159], v[196:199], v[54:57]
	v_mfma_f32_16x16x32_bf16 v[46:49], v[164:167], v[196:199], v[46:49]
	v_mfma_f32_16x16x32_bf16 v[38:41], v[156:159], v[204:207], v[38:41]
	v_mfma_f32_16x16x32_bf16 v[30:33], v[164:167], v[204:207], v[30:33]
	v_mfma_f32_16x16x32_bf16 v[22:25], v[156:159], v[212:215], v[22:25]
	v_mfma_f32_16x16x32_bf16 v[14:17], v[164:167], v[212:215], v[14:17]
	v_mfma_f32_16x16x32_bf16 v[62:65], v[160:163], v[192:195], v[62:65]
	v_mfma_f32_16x16x32_bf16 v[58:61], v[168:171], v[192:195], v[58:61]
	v_mfma_f32_16x16x32_bf16 v[54:57], v[160:163], v[200:203], v[54:57]
	v_mfma_f32_16x16x32_bf16 v[46:49], v[168:171], v[200:203], v[46:49]
	v_mfma_f32_16x16x32_bf16 v[38:41], v[160:163], v[208:211], v[38:41]
	v_mfma_f32_16x16x32_bf16 v[30:33], v[168:171], v[208:211], v[30:33]
	v_mfma_f32_16x16x32_bf16 v[22:25], v[160:163], v[216:219], v[22:25]
	v_mfma_f32_16x16x32_bf16 v[14:17], v[168:171], v[216:219], v[14:17]
	s_setprio 0
	s_setprio 1
	v_mfma_f32_16x16x32_bf16 v[50:53], v[172:175], v[188:191], v[50:53]
	v_mfma_f32_16x16x32_bf16 v[42:45], v[180:183], v[188:191], v[42:45]
	v_mfma_f32_16x16x32_bf16 v[34:37], v[172:175], v[196:199], v[34:37]
	v_mfma_f32_16x16x32_bf16 v[26:29], v[180:183], v[196:199], v[26:29]
	v_mfma_f32_16x16x32_bf16 v[18:21], v[172:175], v[204:207], v[18:21]
	v_mfma_f32_16x16x32_bf16 v[10:13], v[180:183], v[204:207], v[10:13]
	v_mfma_f32_16x16x32_bf16 v[6:9], v[172:175], v[212:215], v[6:9]
	v_mfma_f32_16x16x32_bf16 v[2:5], v[180:183], v[212:215], v[2:5]
	v_mfma_f32_16x16x32_bf16 v[50:53], v[176:179], v[192:195], v[50:53]
	v_mfma_f32_16x16x32_bf16 v[42:45], v[184:187], v[192:195], v[42:45]
	v_mfma_f32_16x16x32_bf16 v[34:37], v[176:179], v[200:203], v[34:37]
	v_mfma_f32_16x16x32_bf16 v[26:29], v[184:187], v[200:203], v[26:29]
	v_mfma_f32_16x16x32_bf16 v[18:21], v[176:179], v[208:211], v[18:21]
	v_mfma_f32_16x16x32_bf16 v[10:13], v[184:187], v[208:211], v[10:13]
	v_mfma_f32_16x16x32_bf16 v[6:9], v[176:179], v[216:219], v[6:9]
	v_mfma_f32_16x16x32_bf16 v[2:5], v[184:187], v[216:219], v[2:5]
	s_setprio 0
	s_barrier
	ds_read_b128 v[156:159], v153
	ds_read_b128 v[160:163], v153 offset:1024
	ds_read_b128 v[164:167], v153 offset:2048
	ds_read_b128 v[168:171], v153 offset:3072
	ds_read_b128 v[172:175], v154
	ds_read_b128 v[176:179], v154 offset:1024
	ds_read_b128 v[180:183], v154 offset:2048
	ds_read_b128 v[184:187], v154 offset:3072
	s_add_u32 s26, s26, 0x80000
	s_addc_u32 s27, s27, 0
	s_mov_b32 m0, s33
	v_lshl_add_u64 v[226:227], s[26:27], 0, v[136:137]
	ds_read_b128 v[188:191], v151 offset:32768
	ds_read_b128 v[192:195], v151 offset:33792
	ds_read_b128 v[196:199], v151 offset:34816
	ds_read_b128 v[200:203], v151 offset:35840
	ds_read_b128 v[204:207], v151 offset:36864
	ds_read_b128 v[208:211], v151 offset:37888
	ds_read_b128 v[212:215], v151 offset:38912
	ds_read_b128 v[216:219], v151 offset:39936
	global_load_lds_dwordx4 v[226:227], off
	v_lshl_add_u64 v[226:227], s[26:27], 0, v[132:133]
	s_mov_b32 m0, s34
	s_nop 0
	global_load_lds_dwordx4 v[226:227], off
	s_waitcnt vmcnt(8) lgkmcnt(0)
	s_setprio 1
	s_barrier
	v_mfma_f32_16x16x32_bf16 v[126:129], v[156:159], v[188:191], v[126:129]
	v_mfma_f32_16x16x32_bf16 v[122:125], v[164:167], v[188:191], v[122:125]
	v_mfma_f32_16x16x32_bf16 v[118:121], v[156:159], v[196:199], v[118:121]
	v_mfma_f32_16x16x32_bf16 v[110:113], v[164:167], v[196:199], v[110:113]
	v_mfma_f32_16x16x32_bf16 v[102:105], v[156:159], v[204:207], v[102:105]
	v_mfma_f32_16x16x32_bf16 v[94:97], v[164:167], v[204:207], v[94:97]
	v_mfma_f32_16x16x32_bf16 v[86:89], v[156:159], v[212:215], v[86:89]
	v_mfma_f32_16x16x32_bf16 v[78:81], v[164:167], v[212:215], v[78:81]
	v_mfma_f32_16x16x32_bf16 v[126:129], v[160:163], v[192:195], v[126:129]
	v_mfma_f32_16x16x32_bf16 v[122:125], v[168:171], v[192:195], v[122:125]
	v_mfma_f32_16x16x32_bf16 v[118:121], v[160:163], v[200:203], v[118:121]
	v_mfma_f32_16x16x32_bf16 v[110:113], v[168:171], v[200:203], v[110:113]
	v_mfma_f32_16x16x32_bf16 v[102:105], v[160:163], v[208:211], v[102:105]
	v_mfma_f32_16x16x32_bf16 v[94:97], v[168:171], v[208:211], v[94:97]
	v_mfma_f32_16x16x32_bf16 v[86:89], v[160:163], v[216:219], v[86:89]
	v_mfma_f32_16x16x32_bf16 v[78:81], v[168:171], v[216:219], v[78:81]
	s_setprio 0
	s_setprio 1
	v_mfma_f32_16x16x32_bf16 v[114:117], v[172:175], v[188:191], v[114:117]
	v_mfma_f32_16x16x32_bf16 v[106:109], v[180:183], v[188:191], v[106:109]
	v_mfma_f32_16x16x32_bf16 v[98:101], v[172:175], v[196:199], v[98:101]
	v_mfma_f32_16x16x32_bf16 v[90:93], v[180:183], v[196:199], v[90:93]
	v_mfma_f32_16x16x32_bf16 v[82:85], v[172:175], v[204:207], v[82:85]
	v_mfma_f32_16x16x32_bf16 v[74:77], v[180:183], v[204:207], v[74:77]
	v_mfma_f32_16x16x32_bf16 v[70:73], v[172:175], v[212:215], v[70:73]
	v_mfma_f32_16x16x32_bf16 v[66:69], v[180:183], v[212:215], v[66:69]
	v_mfma_f32_16x16x32_bf16 v[114:117], v[176:179], v[192:195], v[114:117]
	v_mfma_f32_16x16x32_bf16 v[106:109], v[184:187], v[192:195], v[106:109]
	v_mfma_f32_16x16x32_bf16 v[98:101], v[176:179], v[200:203], v[98:101]
	v_mfma_f32_16x16x32_bf16 v[90:93], v[184:187], v[200:203], v[90:93]
	v_mfma_f32_16x16x32_bf16 v[82:85], v[176:179], v[208:211], v[82:85]
	v_mfma_f32_16x16x32_bf16 v[74:77], v[184:187], v[208:211], v[74:77]
	v_mfma_f32_16x16x32_bf16 v[70:73], v[176:179], v[216:219], v[70:73]
	v_mfma_f32_16x16x32_bf16 v[66:69], v[184:187], v[216:219], v[66:69]
	s_setprio 0
	s_barrier
; #define PG8_STAGE(bufoff, gbase, voff) do { _Pragma("unroll") for (int _i = 0; _i < 2; ++_i) \
;         __builtin_amdgcn_global_load_lds((const unsigned*)((const char*)(gbase) + (voff)[_i]), (LAS unsigned*)(lds + (bufoff) + ldsw + _i * 8192), 16, 0, 0); } while (0)
; #define PG8_LDA(dst, b, h) do { _Pragma("unroll") for (int m = 0; m < 4; ++m) _Pragma("unroll") for (int k = 0; k < 2; ++k) dst[m][k] = *(const LAS bf16x8*)(lds + PG8_SA(b, h) + aoff + m * 2048 + k * 1024); } while (0)
; #define PG8_MMA(ai, bj, At, Bt) do { __builtin_amdgcn_s_setprio(1); _Pragma("unroll") for (int m = 0; m < 4; ++m) _Pragma("unroll") for (int n = 0; n < 2; ++n) _Pragma("unroll") for (int k = 0; k < 2; ++k) \
;         acc[ai][bj][m][n] = __builtin_amdgcn_mfma_f32_16x16x32_bf16(Bt[n][k], At[m][k], acc[ai][bj][m][n], 0, 0, 0); __builtin_amdgcn_s_setprio(0); } while (0)
; #define PG8_WAIT_V(n) asm volatile("s_waitcnt vmcnt(" #n ")" ::: "memory")
; #define PG8_WAIT_L(n) asm volatile("s_waitcnt lgkmcnt(" #n ")" ::: "memory")
; #define PG8_BAR __builtin_amdgcn_s_barrier()
; #define PG8_SCHED __builtin_amdgcn_sched_barrier(0)
; template <class Epi, class Sched, bool ALIGN_EPI = false, bool SP2 = false>
; __device__ __forceinline__ void gemm_phase(LAS unsigned char* lds, const Gemm g, const Sched& S, const Epi& E) {
;     ...
;             PG8_LDA(At, 1, 1); PG8_STAGE(PG8_SB(1, 0), b3, voffB); PG8_STAGE(PG8_SB(1, 1), b3 + hstepB, voffB); PG8_STAGE(PG8_SA(1, 0), a3, voffA);
;             PG8_WAIT_V(8); PG8_WAIT_L(0); PG8_BAR; PG8_MMA(1, 0, At, B0); PG8_MMA(1, 1, At, B1); PG8_BAR; PG8_SCHED;
;     ...
;         if constexpr (ALIGN_EPI) { if (wr == 0) PG8_BAR; }
	s_add_i32 s26, s44, s28
	v_lshl_add_u64 v[146:147], v[146:147], 0, s[6:7]
	s_mov_b32 m0, s26
	ds_read_b128 v[188:191], v151 offset:49152
	ds_read_b128 v[192:195], v151 offset:50176
	ds_read_b128 v[196:199], v151 offset:51200
	ds_read_b128 v[200:203], v151 offset:52224
	ds_read_b128 v[204:207], v151 offset:53248
	ds_read_b128 v[208:211], v151 offset:54272
	ds_read_b128 v[212:215], v151 offset:55296
	ds_read_b128 v[216:219], v151 offset:56320
	global_load_lds_dwordx4 v[146:147], off
	s_add_i32 m0, s26, 0x2000
	s_add_u32 s24, s24, 0x80080
	v_lshl_add_u64 v[146:147], v[220:221], 0, s[6:7]
	s_addc_u32 s25, s25, 0
	s_add_i32 s26, s45, s28
	global_load_lds_dwordx4 v[146:147], off
	v_lshl_add_u64 v[146:147], s[24:25], 0, v[134:135]
	s_mov_b32 m0, s26
	s_nop 0
	global_load_lds_dwordx4 v[146:147], off
	v_lshl_add_u64 v[146:147], s[24:25], 0, v[130:131]
	s_add_i32 m0, s26, 0x2000
	s_nop 0
	global_load_lds_dwordx4 v[146:147], off
	v_lshl_add_u64 v[146:147], v[222:223], 0, s[6:7]
	s_mov_b32 m0, s36
	s_nop 0
	global_load_lds_dwordx4 v[146:147], off
	v_lshl_add_u64 v[146:147], v[224:225], 0, s[6:7]
	s_mov_b32 m0, s37
	s_nop 0
	global_load_lds_dwordx4 v[146:147], off
	s_waitcnt vmcnt(8) lgkmcnt(0)
	s_setprio 1
	s_barrier
	v_mfma_f32_16x16x32_bf16 v[62:65], v[156:159], v[188:191], v[62:65]
	v_mfma_f32_16x16x32_bf16 v[58:61], v[164:167], v[188:191], v[58:61]
	v_mfma_f32_16x16x32_bf16 v[54:57], v[156:159], v[196:199], v[54:57]
	v_mfma_f32_16x16x32_bf16 v[46:49], v[164:167], v[196:199], v[46:49]
	v_mfma_f32_16x16x32_bf16 v[38:41], v[156:159], v[204:207], v[38:41]
	v_mfma_f32_16x16x32_bf16 v[30:33], v[164:167], v[204:207], v[30:33]
	v_mfma_f32_16x16x32_bf16 v[22:25], v[156:159], v[212:215], v[22:25]
	v_mfma_f32_16x16x32_bf16 v[14:17], v[164:167], v[212:215], v[14:17]
	v_mfma_f32_16x16x32_bf16 v[62:65], v[160:163], v[192:195], v[62:65]
	v_mfma_f32_16x16x32_bf16 v[58:61], v[168:171], v[192:195], v[58:61]
	v_mfma_f32_16x16x32_bf16 v[54:57], v[160:163], v[200:203], v[54:57]
	v_mfma_f32_16x16x32_bf16 v[46:49], v[168:171], v[200:203], v[46:49]
	v_mfma_f32_16x16x32_bf16 v[38:41], v[160:163], v[208:211], v[38:41]
	v_mfma_f32_16x16x32_bf16 v[30:33], v[168:171], v[208:211], v[30:33]
	v_mfma_f32_16x16x32_bf16 v[22:25], v[160:163], v[216:219], v[22:25]
	v_mfma_f32_16x16x32_bf16 v[14:17], v[168:171], v[216:219], v[14:17]
	s_setprio 0
	s_setprio 1
	v_mfma_f32_16x16x32_bf16 v[50:53], v[172:175], v[188:191], v[50:53]
	v_mfma_f32_16x16x32_bf16 v[42:45], v[180:183], v[188:191], v[42:45]
	v_mfma_f32_16x16x32_bf16 v[34:37], v[172:175], v[196:199], v[34:37]
	v_mfma_f32_16x16x32_bf16 v[26:29], v[180:183], v[196:199], v[26:29]
	v_mfma_f32_16x16x32_bf16 v[18:21], v[172:175], v[204:207], v[18:21]
	v_mfma_f32_16x16x32_bf16 v[10:13], v[180:183], v[204:207], v[10:13]
	v_mfma_f32_16x16x32_bf16 v[6:9], v[172:175], v[212:215], v[6:9]
	v_mfma_f32_16x16x32_bf16 v[2:5], v[180:183], v[212:215], v[2:5]
	v_mfma_f32_16x16x32_bf16 v[50:53], v[176:179], v[192:195], v[50:53]
	v_mfma_f32_16x16x32_bf16 v[42:45], v[184:187], v[192:195], v[42:45]
	v_mfma_f32_16x16x32_bf16 v[34:37], v[176:179], v[200:203], v[34:37]
	v_mfma_f32_16x16x32_bf16 v[26:29], v[184:187], v[200:203], v[26:29]
	v_mfma_f32_16x16x32_bf16 v[18:21], v[176:179], v[208:211], v[18:21]
	v_mfma_f32_16x16x32_bf16 v[10:13], v[184:187], v[208:211], v[10:13]
	v_mfma_f32_16x16x32_bf16 v[6:9], v[176:179], v[216:219], v[6:9]
	v_mfma_f32_16x16x32_bf16 v[2:5], v[184:187], v[216:219], v[2:5]
	s_add_i32 s58, s58, 2
	s_add_u32 s22, s22, 0x100
	s_addc_u32 s23, s23, 0
	s_add_u32 s51, s51, 0x100
	s_addc_u32 s55, s55, 0
	s_setprio 0
	s_barrier
	s_cmp_gt_u32 s58, 29
	s_cbranch_scc0 .LBB0_349
	s_and_b64 vcc, exec, s[10:11]
	s_cbranch_vccz .LBB0_352
	s_barrier

; #define PG8_STAGE(bufoff, gbase, voff) do { _Pragma("unroll") for (int _i = 0; _i < 2; ++_i) \
;         __builtin_amdgcn_global_load_lds((const unsigned*)((const char*)(gbase) + (voff)[_i]), (LAS unsigned*)(lds + (bufoff) + ldsw + _i * 8192), 16, 0, 0); } while (0)
; #define PG8_LDA(dst, b, h) do { _Pragma("unroll") for (int m = 0; m < 4; ++m) _Pragma("unroll") for (int k = 0; k < 2; ++k) dst[m][k] = *(const LAS bf16x8*)(lds + PG8_SA(b, h) + aoff + m * 2048 + k * 1024); } while (0)
; #define PG8_LDB(dst, b, h) do { _Pragma("unroll") for (int n = 0; n < 2; ++n) _Pragma("unroll") for (int k = 0; k < 2; ++k) dst[n][k] = *(const LAS bf16x8*)(lds + PG8_SB(b, h) + boff + n * 2048 + k * 1024); } while (0)
; #define PG8_MMA(ai, bj, At, Bt) do { __builtin_amdgcn_s_setprio(1); _Pragma("unroll") for (int m = 0; m < 4; ++m) _Pragma("unroll") for (int n = 0; n < 2; ++n) _Pragma("unroll") for (int k = 0; k < 2; ++k) \
;         acc[ai][bj][m][n] = __builtin_amdgcn_mfma_f32_16x16x32_bf16(Bt[n][k], At[m][k], acc[ai][bj][m][n], 0, 0, 0); __builtin_amdgcn_s_setprio(0); } while (0)
; #define PG8_WAIT_V(n) asm volatile("s_waitcnt vmcnt(" #n ")" ::: "memory")
; #define PG8_WAIT_L(n) asm volatile("s_waitcnt lgkmcnt(" #n ")" ::: "memory")
; template <class Epi, class Sched, bool ALIGN_EPI = false, bool SP2 = false>
; __device__ __forceinline__ void gemm_phase(LAS unsigned char* lds, const Gemm g, const Sched& S, const Epi& E) {
;     ...
;         for (int t = 0; t < nt; t += 2) {
;             const bool last = (t == nt - 2);
;             const char* a1 = cA + (size_t)(t + 1) * kstep;
;             const char* a2 = last ? nA : cA + (size_t)(t + 2) * kstep; const char* b2 = last ? nB : cB + (size_t)(t + 2) * kstep;
;             const char* a3 = a2 + kstep; const char* b3 = b2 + kstep;
;             if (last && has_next) S.a_ready(nxt);
;             if constexpr (SP2) {
;             PG8_LDB(B0, 0, 0); PG8_LDB(B1, 0, 1); PG8_SCHED; PG8_LDA(At, 0, 0); PG8_STAGE(PG8_SA(1, 1), a1 + hstepA, voffA);
;             PG8_WAIT_V(8); PG8_WAIT_L(0); PG8_BAR; PG8_MMA(0, 0, At, B0); PG8_MMA(0, 1, At, B1); PG8_BAR; PG8_SCHED;
;             PG8_LDA(At, 0, 1); PG8_STAGE(PG8_SB(0, 0), b2, voffB); PG8_STAGE(PG8_SB(0, 1), b2 + hstepB, voffB); PG8_STAGE(PG8_SA(0, 0), a2, voffA);
;             PG8_WAIT_V(8); PG8_WAIT_L(0); PG8_BAR; PG8_MMA(1, 0, At, B0); PG8_MMA(1, 1, At, B1); PG8_BAR; PG8_SCHED;
.LBB0_560:
	s_add_u32 s27, s20, s26
	s_addc_u32 s34, s21, 0
	s_add_u32 s30, s27, 0x100
	s_addc_u32 s31, s34, 0
	s_and_b64 s[28:29], s[24:25], exec
	s_cselect_b32 s29, s1, s31
	s_cselect_b32 s28, s0, s30
	s_add_u32 s26, s16, s26
	s_addc_u32 s30, s17, 0
	s_add_u32 s26, s26, 0x100
	s_addc_u32 s30, s30, 0
	s_and_b64 s[24:25], s[24:25], exec
	s_cselect_b32 s31, s19, s30
	s_cselect_b32 s30, s18, s26
	s_add_u32 s36, s27, 0x18080
	ds_read_b128 v[154:157], v147
	ds_read_b128 v[158:161], v147 offset:1024
	ds_read_b128 v[162:165], v147 offset:2048
	ds_read_b128 v[166:169], v147 offset:3072
	ds_read_b128 v[170:173], v148
	ds_read_b128 v[174:177], v148 offset:1024
	ds_read_b128 v[178:181], v148 offset:2048
	ds_read_b128 v[182:185], v148 offset:3072
	s_addc_u32 s37, s34, 0
	s_add_i32 s73, s54, s39
	s_add_i32 m0, s40, 0xc000
	s_add_i32 s76, s40, 0xe000
	s_add_i32 s70, s73, 0x2000
	s_add_u32 s34, s30, 0x18000
	s_addc_u32 s35, s31, 0
	s_add_i32 s72, s55, s39
	s_add_i32 s71, s72, 0x2000
	s_add_u32 s26, s28, 0x18000
	s_addc_u32 s27, s29, 0
	s_add_i32 s67, s57, s39
	s_add_i32 s65, s67, 0x2000
	s_add_u32 s24, s30, 0x18080
	s_addc_u32 s25, s31, 0
	s_add_i32 s66, s58, s39
	s_add_i32 s63, s66, 0x2000
	v_lshl_add_u64 v[218:219], s[36:37], 0, v[130:131]
	ds_read_b128 v[186:189], v149
	ds_read_b128 v[190:193], v149 offset:1024
	ds_read_b128 v[194:197], v149 offset:2048
	ds_read_b128 v[198:201], v149 offset:3072
	ds_read_b128 v[202:205], v149 offset:4096
	ds_read_b128 v[206:209], v149 offset:5120
	ds_read_b128 v[210:213], v149 offset:6144
	ds_read_b128 v[214:217], v149 offset:7168
	global_load_lds_dwordx4 v[218:219], off
	v_lshl_add_u64 v[218:219], s[36:37], 0, v[134:135]
	s_mov_b32 m0, s76
	s_nop 0
	global_load_lds_dwordx4 v[218:219], off
	s_waitcnt vmcnt(8) lgkmcnt(0)
	s_setprio 1
	s_barrier
	v_mfma_f32_16x16x32_bf16 v[126:129], v[154:157], v[186:189], v[126:129]
	v_mfma_f32_16x16x32_bf16 v[122:125], v[162:165], v[186:189], v[122:125]
	v_mfma_f32_16x16x32_bf16 v[118:121], v[154:157], v[194:197], v[118:121]
	v_mfma_f32_16x16x32_bf16 v[110:113], v[162:165], v[194:197], v[110:113]
	v_mfma_f32_16x16x32_bf16 v[102:105], v[154:157], v[202:205], v[102:105]
	v_mfma_f32_16x16x32_bf16 v[94:97], v[162:165], v[202:205], v[94:97]
	v_mfma_f32_16x16x32_bf16 v[86:89], v[154:157], v[210:213], v[86:89]
	v_mfma_f32_16x16x32_bf16 v[78:81], v[162:165], v[210:213], v[78:81]
	v_mfma_f32_16x16x32_bf16 v[126:129], v[158:161], v[190:193], v[126:129]
	v_mfma_f32_16x16x32_bf16 v[122:125], v[166:169], v[190:193], v[122:125]
	v_mfma_f32_16x16x32_bf16 v[118:121], v[158:161], v[198:201], v[118:121]
	v_mfma_f32_16x16x32_bf16 v[110:113], v[166:169], v[198:201], v[110:113]
	v_mfma_f32_16x16x32_bf16 v[102:105], v[158:161], v[206:209], v[102:105]
	v_mfma_f32_16x16x32_bf16 v[94:97], v[166:169], v[206:209], v[94:97]
	v_mfma_f32_16x16x32_bf16 v[86:89], v[158:161], v[214:217], v[86:89]
	v_mfma_f32_16x16x32_bf16 v[78:81], v[166:169], v[214:217], v[78:81]
	s_setprio 0
	s_setprio 1
	v_mfma_f32_16x16x32_bf16 v[114:117], v[170:173], v[186:189], v[114:117]
	v_mfma_f32_16x16x32_bf16 v[106:109], v[178:181], v[186:189], v[106:109]
	v_mfma_f32_16x16x32_bf16 v[98:101], v[170:173], v[194:197], v[98:101]
	v_mfma_f32_16x16x32_bf16 v[90:93], v[178:181], v[194:197], v[90:93]
	v_mfma_f32_16x16x32_bf16 v[82:85], v[170:173], v[202:205], v[82:85]
	v_mfma_f32_16x16x32_bf16 v[74:77], v[178:181], v[202:205], v[74:77]
	v_mfma_f32_16x16x32_bf16 v[70:73], v[170:173], v[210:213], v[70:73]
	v_mfma_f32_16x16x32_bf16 v[66:69], v[178:181], v[210:213], v[66:69]
	v_mfma_f32_16x16x32_bf16 v[114:117], v[174:177], v[190:193], v[114:117]
	v_mfma_f32_16x16x32_bf16 v[106:109], v[182:185], v[190:193], v[106:109]
	v_mfma_f32_16x16x32_bf16 v[98:101], v[174:177], v[198:201], v[98:101]
	v_mfma_f32_16x16x32_bf16 v[90:93], v[182:185], v[198:201], v[90:93]
	v_mfma_f32_16x16x32_bf16 v[82:85], v[174:177], v[206:209], v[82:85]
	v_mfma_f32_16x16x32_bf16 v[74:77], v[182:185], v[206:209], v[74:77]
	v_mfma_f32_16x16x32_bf16 v[70:73], v[174:177], v[214:217], v[70:73]
	v_mfma_f32_16x16x32_bf16 v[66:69], v[182:185], v[214:217], v[66:69]
	s_setprio 0
	s_barrier
	s_mov_b32 m0, s73
	v_lshl_add_u64 v[218:219], s[30:31], 0, v[132:133]
	ds_read_b128 v[186:189], v149 offset:16384
	ds_read_b128 v[190:193], v149 offset:17408
	ds_read_b128 v[194:197], v149 offset:18432
	ds_read_b128 v[198:201], v149 offset:19456
	ds_read_b128 v[202:205], v149 offset:20480
	ds_read_b128 v[206:209], v149 offset:21504
	ds_read_b128 v[210:213], v149 offset:22528
	ds_read_b128 v[214:217], v149 offset:23552
	global_load_lds_dwordx4 v[218:219], off
	v_lshl_add_u64 v[220:221], s[30:31], 0, v[136:137]
	s_mov_b32 m0, s70
	v_lshl_add_u64 v[222:223], s[34:35], 0, v[132:133]
	global_load_lds_dwordx4 v[220:221], off
	s_mov_b32 m0, s72
	v_lshl_add_u64 v[224:225], s[28:29], 0, v[134:135]
	global_load_lds_dwordx4 v[222:223], off
	v_lshl_add_u64 v[222:223], s[34:35], 0, v[136:137]
	s_mov_b32 m0, s71
	s_nop 0
	global_load_lds_dwordx4 v[222:223], off
	v_lshl_add_u64 v[222:223], s[28:29], 0, v[130:131]
	s_mov_b32 m0, s40
	s_nop 0
	global_load_lds_dwordx4 v[222:223], off
	s_mov_b32 m0, s33
	s_nop 0
	global_load_lds_dwordx4 v[224:225], off
	s_waitcnt vmcnt(8) lgkmcnt(0)
	s_setprio 1
	s_barrier
; #define PG8_STAGE(bufoff, gbase, voff) do { _Pragma("unroll") for (int _i = 0; _i < 2; ++_i) \
;         __builtin_amdgcn_global_load_lds((const unsigned*)((const char*)(gbase) + (voff)[_i]), (LAS unsigned*)(lds + (bufoff) + ldsw + _i * 8192), 16, 0, 0); } while (0)
; #define PG8_LDA(dst, b, h) do { _Pragma("unroll") for (int m = 0; m < 4; ++m) _Pragma("unroll") for (int k = 0; k < 2; ++k) dst[m][k] = *(const LAS bf16x8*)(lds + PG8_SA(b, h) + aoff + m * 2048 + k * 1024); } while (0)
; #define PG8_LDB(dst, b, h) do { _Pragma("unroll") for (int n = 0; n < 2; ++n) _Pragma("unroll") for (int k = 0; k < 2; ++k) dst[n][k] = *(const LAS bf16x8*)(lds + PG8_SB(b, h) + boff + n * 2048 + k * 1024); } while (0)
; #define PG8_MMA(ai, bj, At, Bt) do { __builtin_amdgcn_s_setprio(1); _Pragma("unroll") for (int m = 0; m < 4; ++m) _Pragma("unroll") for (int n = 0; n < 2; ++n) _Pragma("unroll") for (int k = 0; k < 2; ++k) \
;         acc[ai][bj][m][n] = __builtin_amdgcn_mfma_f32_16x16x32_bf16(Bt[n][k], At[m][k], acc[ai][bj][m][n], 0, 0, 0); __builtin_amdgcn_s_setprio(0); } while (0)
; #define PG8_WAIT_V(n) asm volatile("s_waitcnt vmcnt(" #n ")" ::: "memory")
; #define PG8_WAIT_L(n) asm volatile("s_waitcnt lgkmcnt(" #n ")" ::: "memory")
; #define PG8_BAR __builtin_amdgcn_s_barrier()
; #define PG8_SCHED __builtin_amdgcn_sched_barrier(0)
; template <class Epi, class Sched, bool ALIGN_EPI = false, bool SP2 = false>
; __device__ __forceinline__ void gemm_phase(LAS unsigned char* lds, const Gemm g, const Sched& S, const Epi& E) {
;     ...
;             PG8_WAIT_V(8); PG8_WAIT_L(0); PG8_BAR; PG8_MMA(1, 0, At, B0); PG8_MMA(1, 1, At, B1); PG8_BAR; PG8_SCHED;
;             PG8_LDB(B0, 1, 0); PG8_LDB(B1, 1, 1); PG8_SCHED; PG8_LDA(At, 1, 0); PG8_STAGE(PG8_SA(0, 1), a2 + hstepA, voffA);
;             PG8_WAIT_V(8); PG8_WAIT_L(0); PG8_BAR; PG8_MMA(0, 0, At, B0); PG8_MMA(0, 1, At, B1); PG8_BAR; PG8_SCHED;
	v_mfma_f32_16x16x32_bf16 v[62:65], v[154:157], v[186:189], v[62:65]
	v_mfma_f32_16x16x32_bf16 v[58:61], v[162:165], v[186:189], v[58:61]
	v_mfma_f32_16x16x32_bf16 v[54:57], v[154:157], v[194:197], v[54:57]
	v_mfma_f32_16x16x32_bf16 v[46:49], v[162:165], v[194:197], v[46:49]
	v_mfma_f32_16x16x32_bf16 v[38:41], v[154:157], v[202:205], v[38:41]
	v_mfma_f32_16x16x32_bf16 v[30:33], v[162:165], v[202:205], v[30:33]
	v_mfma_f32_16x16x32_bf16 v[22:25], v[154:157], v[210:213], v[22:25]
	v_mfma_f32_16x16x32_bf16 v[14:17], v[162:165], v[210:213], v[14:17]
	v_mfma_f32_16x16x32_bf16 v[62:65], v[158:161], v[190:193], v[62:65]
	v_mfma_f32_16x16x32_bf16 v[58:61], v[166:169], v[190:193], v[58:61]
	v_mfma_f32_16x16x32_bf16 v[54:57], v[158:161], v[198:201], v[54:57]
	v_mfma_f32_16x16x32_bf16 v[46:49], v[166:169], v[198:201], v[46:49]
	v_mfma_f32_16x16x32_bf16 v[38:41], v[158:161], v[206:209], v[38:41]
	v_mfma_f32_16x16x32_bf16 v[30:33], v[166:169], v[206:209], v[30:33]
	v_mfma_f32_16x16x32_bf16 v[22:25], v[158:161], v[214:217], v[22:25]
	v_mfma_f32_16x16x32_bf16 v[14:17], v[166:169], v[214:217], v[14:17]
	s_setprio 0
	s_setprio 1
	v_mfma_f32_16x16x32_bf16 v[50:53], v[170:173], v[186:189], v[50:53]
	v_mfma_f32_16x16x32_bf16 v[42:45], v[178:181], v[186:189], v[42:45]
	v_mfma_f32_16x16x32_bf16 v[34:37], v[170:173], v[194:197], v[34:37]
	v_mfma_f32_16x16x32_bf16 v[26:29], v[178:181], v[194:197], v[26:29]
	v_mfma_f32_16x16x32_bf16 v[18:21], v[170:173], v[202:205], v[18:21]
	v_mfma_f32_16x16x32_bf16 v[10:13], v[178:181], v[202:205], v[10:13]
	v_mfma_f32_16x16x32_bf16 v[6:9], v[170:173], v[210:213], v[6:9]
	v_mfma_f32_16x16x32_bf16 v[2:5], v[178:181], v[210:213], v[2:5]
	v_mfma_f32_16x16x32_bf16 v[50:53], v[174:177], v[190:193], v[50:53]
	v_mfma_f32_16x16x32_bf16 v[42:45], v[182:185], v[190:193], v[42:45]
	v_mfma_f32_16x16x32_bf16 v[34:37], v[174:177], v[198:201], v[34:37]
	v_mfma_f32_16x16x32_bf16 v[26:29], v[182:185], v[198:201], v[26:29]
	v_mfma_f32_16x16x32_bf16 v[18:21], v[174:177], v[206:209], v[18:21]
	v_mfma_f32_16x16x32_bf16 v[10:13], v[182:185], v[206:209], v[10:13]
	v_mfma_f32_16x16x32_bf16 v[6:9], v[174:177], v[214:217], v[6:9]
	v_mfma_f32_16x16x32_bf16 v[2:5], v[182:185], v[214:217], v[2:5]
	s_setprio 0
	s_barrier
	ds_read_b128 v[154:157], v150
	ds_read_b128 v[158:161], v150 offset:1024
	ds_read_b128 v[162:165], v150 offset:2048
	ds_read_b128 v[166:169], v150 offset:3072
	ds_read_b128 v[170:173], v151
	ds_read_b128 v[174:177], v151 offset:1024
	ds_read_b128 v[178:181], v151 offset:2048
	ds_read_b128 v[182:185], v151 offset:3072
	s_mov_b32 m0, s41
	v_lshl_add_u64 v[226:227], s[26:27], 0, v[130:131]
	ds_read_b128 v[186:189], v149 offset:32768
	ds_read_b128 v[190:193], v149 offset:33792
	ds_read_b128 v[194:197], v149 offset:34816
	ds_read_b128 v[198:201], v149 offset:35840
	ds_read_b128 v[202:205], v149 offset:36864
	ds_read_b128 v[206:209], v149 offset:37888
	ds_read_b128 v[210:213], v149 offset:38912
	ds_read_b128 v[214:217], v149 offset:39936
	global_load_lds_dwordx4 v[226:227], off
	v_lshl_add_u64 v[226:227], s[26:27], 0, v[134:135]
	s_mov_b32 m0, s44
	s_nop 0
	global_load_lds_dwordx4 v[226:227], off
	s_waitcnt vmcnt(8) lgkmcnt(0)
	s_setprio 1
	s_barrier
	v_mfma_f32_16x16x32_bf16 v[126:129], v[154:157], v[186:189], v[126:129]
	v_mfma_f32_16x16x32_bf16 v[122:125], v[162:165], v[186:189], v[122:125]
	v_mfma_f32_16x16x32_bf16 v[118:121], v[154:157], v[194:197], v[118:121]
	v_mfma_f32_16x16x32_bf16 v[110:113], v[162:165], v[194:197], v[110:113]
	v_mfma_f32_16x16x32_bf16 v[102:105], v[154:157], v[202:205], v[102:105]
	v_mfma_f32_16x16x32_bf16 v[94:97], v[162:165], v[202:205], v[94:97]
	v_mfma_f32_16x16x32_bf16 v[86:89], v[154:157], v[210:213], v[86:89]
	v_mfma_f32_16x16x32_bf16 v[78:81], v[162:165], v[210:213], v[78:81]
	v_mfma_f32_16x16x32_bf16 v[126:129], v[158:161], v[190:193], v[126:129]
	v_mfma_f32_16x16x32_bf16 v[122:125], v[166:169], v[190:193], v[122:125]
	v_mfma_f32_16x16x32_bf16 v[118:121], v[158:161], v[198:201], v[118:121]
	v_mfma_f32_16x16x32_bf16 v[110:113], v[166:169], v[198:201], v[110:113]
	v_mfma_f32_16x16x32_bf16 v[102:105], v[158:161], v[206:209], v[102:105]
	v_mfma_f32_16x16x32_bf16 v[94:97], v[166:169], v[206:209], v[94:97]
	v_mfma_f32_16x16x32_bf16 v[86:89], v[158:161], v[214:217], v[86:89]
	v_mfma_f32_16x16x32_bf16 v[78:81], v[166:169], v[214:217], v[78:81]
	s_setprio 0
	s_setprio 1
	v_mfma_f32_16x16x32_bf16 v[114:117], v[170:173], v[186:189], v[114:117]
	v_mfma_f32_16x16x32_bf16 v[106:109], v[178:181], v[186:189], v[106:109]
	v_mfma_f32_16x16x32_bf16 v[98:101], v[170:173], v[194:197], v[98:101]
	v_mfma_f32_16x16x32_bf16 v[90:93], v[178:181], v[194:197], v[90:93]
	v_mfma_f32_16x16x32_bf16 v[82:85], v[170:173], v[202:205], v[82:85]
	v_mfma_f32_16x16x32_bf16 v[74:77], v[178:181], v[202:205], v[74:77]
	v_mfma_f32_16x16x32_bf16 v[70:73], v[170:173], v[210:213], v[70:73]
	v_mfma_f32_16x16x32_bf16 v[66:69], v[178:181], v[210:213], v[66:69]
	v_mfma_f32_16x16x32_bf16 v[114:117], v[174:177], v[190:193], v[114:117]
	v_mfma_f32_16x16x32_bf16 v[106:109], v[182:185], v[190:193], v[106:109]
	v_mfma_f32_16x16x32_bf16 v[98:101], v[174:177], v[198:201], v[98:101]
	v_mfma_f32_16x16x32_bf16 v[90:93], v[182:185], v[198:201], v[90:93]
	v_mfma_f32_16x16x32_bf16 v[82:85], v[174:177], v[206:209], v[82:85]
	v_mfma_f32_16x16x32_bf16 v[74:77], v[182:185], v[206:209], v[74:77]
	v_mfma_f32_16x16x32_bf16 v[70:73], v[174:177], v[214:217], v[70:73]
	v_mfma_f32_16x16x32_bf16 v[66:69], v[182:185], v[214:217], v[66:69]
	s_setprio 0
	s_barrier
; #define PG8_STAGE(bufoff, gbase, voff) do { _Pragma("unroll") for (int _i = 0; _i < 2; ++_i) \
;         __builtin_amdgcn_global_load_lds((const unsigned*)((const char*)(gbase) + (voff)[_i]), (LAS unsigned*)(lds + (bufoff) + ldsw + _i * 8192), 16, 0, 0); } while (0)
; #define PG8_LDA(dst, b, h) do { _Pragma("unroll") for (int m = 0; m < 4; ++m) _Pragma("unroll") for (int k = 0; k < 2; ++k) dst[m][k] = *(const LAS bf16x8*)(lds + PG8_SA(b, h) + aoff + m * 2048 + k * 1024); } while (0)
; #define PG8_MMA(ai, bj, At, Bt) do { __builtin_amdgcn_s_setprio(1); _Pragma("unroll") for (int m = 0; m < 4; ++m) _Pragma("unroll") for (int n = 0; n < 2; ++n) _Pragma("unroll") for (int k = 0; k < 2; ++k) \
;         acc[ai][bj][m][n] = __builtin_amdgcn_mfma_f32_16x16x32_bf16(Bt[n][k], At[m][k], acc[ai][bj][m][n], 0, 0, 0); __builtin_amdgcn_s_setprio(0); } while (0)
; #define PG8_WAIT_V(n) asm volatile("s_waitcnt vmcnt(" #n ")" ::: "memory")
; #define PG8_WAIT_L(n) asm volatile("s_waitcnt lgkmcnt(" #n ")" ::: "memory")
; #define PG8_BAR __builtin_amdgcn_s_barrier()
; #define PG8_SCHED __builtin_amdgcn_sched_barrier(0)
; template <class Epi, class Sched, bool ALIGN_EPI = false, bool SP2 = false>
; __device__ __forceinline__ void gemm_phase(LAS unsigned char* lds, const Gemm g, const Sched& S, const Epi& E) {
;     ...
;             PG8_LDA(At, 1, 1); PG8_STAGE(PG8_SB(1, 0), b3, voffB); PG8_STAGE(PG8_SB(1, 1), b3 + hstepB, voffB); PG8_STAGE(PG8_SA(1, 0), a3, voffA);
;             PG8_WAIT_V(8); PG8_WAIT_L(0); PG8_BAR; PG8_MMA(1, 0, At, B0); PG8_MMA(1, 1, At, B1); PG8_BAR; PG8_SCHED;
;     ...
;         if constexpr (ALIGN_EPI) { if (wr == 0) PG8_BAR; }
	s_mov_b32 m0, s67
	v_lshl_add_u64 v[218:219], v[218:219], 0, s[12:13]
	ds_read_b128 v[186:189], v149 offset:49152
	ds_read_b128 v[190:193], v149 offset:50176
	ds_read_b128 v[194:197], v149 offset:51200
	ds_read_b128 v[198:201], v149 offset:52224
	ds_read_b128 v[202:205], v149 offset:53248
	ds_read_b128 v[206:209], v149 offset:54272
	ds_read_b128 v[210:213], v149 offset:55296
	ds_read_b128 v[214:217], v149 offset:56320
	global_load_lds_dwordx4 v[218:219], off
	v_lshl_add_u64 v[218:219], v[220:221], 0, s[12:13]
	s_mov_b32 m0, s65
	s_nop 0
	global_load_lds_dwordx4 v[218:219], off
	v_lshl_add_u64 v[218:219], s[24:25], 0, v[132:133]
	s_mov_b32 m0, s66
	s_nop 0
	global_load_lds_dwordx4 v[218:219], off
	v_lshl_add_u64 v[218:219], s[24:25], 0, v[136:137]
	s_mov_b32 m0, s63
	s_nop 0
	global_load_lds_dwordx4 v[218:219], off
	v_lshl_add_u64 v[218:219], v[222:223], 0, s[12:13]
	s_mov_b32 m0, s45
	s_nop 0
	global_load_lds_dwordx4 v[218:219], off
	v_lshl_add_u64 v[218:219], v[224:225], 0, s[12:13]
	s_mov_b32 m0, s46
	s_nop 0
	global_load_lds_dwordx4 v[218:219], off
	s_waitcnt vmcnt(8) lgkmcnt(0)
	s_setprio 1
	s_barrier
	v_mfma_f32_16x16x32_bf16 v[62:65], v[154:157], v[186:189], v[62:65]
	v_mfma_f32_16x16x32_bf16 v[58:61], v[162:165], v[186:189], v[58:61]
	v_mfma_f32_16x16x32_bf16 v[54:57], v[154:157], v[194:197], v[54:57]
	v_mfma_f32_16x16x32_bf16 v[46:49], v[162:165], v[194:197], v[46:49]
	v_mfma_f32_16x16x32_bf16 v[38:41], v[154:157], v[202:205], v[38:41]
	v_mfma_f32_16x16x32_bf16 v[30:33], v[162:165], v[202:205], v[30:33]
	v_mfma_f32_16x16x32_bf16 v[22:25], v[154:157], v[210:213], v[22:25]
	v_mfma_f32_16x16x32_bf16 v[14:17], v[162:165], v[210:213], v[14:17]
	v_mfma_f32_16x16x32_bf16 v[62:65], v[158:161], v[190:193], v[62:65]
	v_mfma_f32_16x16x32_bf16 v[58:61], v[166:169], v[190:193], v[58:61]
	v_mfma_f32_16x16x32_bf16 v[54:57], v[158:161], v[198:201], v[54:57]
	v_mfma_f32_16x16x32_bf16 v[46:49], v[166:169], v[198:201], v[46:49]
	v_mfma_f32_16x16x32_bf16 v[38:41], v[158:161], v[206:209], v[38:41]
	v_mfma_f32_16x16x32_bf16 v[30:33], v[166:169], v[206:209], v[30:33]
	v_mfma_f32_16x16x32_bf16 v[22:25], v[158:161], v[214:217], v[22:25]
	v_mfma_f32_16x16x32_bf16 v[14:17], v[166:169], v[214:217], v[14:17]
	s_setprio 0
	s_setprio 1
	v_mfma_f32_16x16x32_bf16 v[50:53], v[170:173], v[186:189], v[50:53]
	v_mfma_f32_16x16x32_bf16 v[42:45], v[178:181], v[186:189], v[42:45]
	v_mfma_f32_16x16x32_bf16 v[34:37], v[170:173], v[194:197], v[34:37]
	v_mfma_f32_16x16x32_bf16 v[26:29], v[178:181], v[194:197], v[26:29]
	v_mfma_f32_16x16x32_bf16 v[18:21], v[170:173], v[202:205], v[18:21]
	v_mfma_f32_16x16x32_bf16 v[10:13], v[178:181], v[202:205], v[10:13]
	v_mfma_f32_16x16x32_bf16 v[6:9], v[170:173], v[210:213], v[6:9]
	v_mfma_f32_16x16x32_bf16 v[2:5], v[178:181], v[210:213], v[2:5]
	v_mfma_f32_16x16x32_bf16 v[50:53], v[174:177], v[190:193], v[50:53]
	v_mfma_f32_16x16x32_bf16 v[42:45], v[182:185], v[190:193], v[42:45]
	v_mfma_f32_16x16x32_bf16 v[34:37], v[174:177], v[198:201], v[34:37]
	v_mfma_f32_16x16x32_bf16 v[26:29], v[182:185], v[198:201], v[26:29]
	v_mfma_f32_16x16x32_bf16 v[18:21], v[174:177], v[206:209], v[18:21]
	v_mfma_f32_16x16x32_bf16 v[10:13], v[182:185], v[206:209], v[10:13]
	v_mfma_f32_16x16x32_bf16 v[6:9], v[174:177], v[214:217], v[6:9]
	v_mfma_f32_16x16x32_bf16 v[2:5], v[182:185], v[214:217], v[2:5]
	s_setprio 0
	s_barrier
	s_movk_i32 s26, 0x100
	s_andn2_b64 vcc, exec, s[22:23]
	s_mov_b64 s[24:25], -1
	s_mov_b64 s[22:23], 0
	s_cbranch_vccz .LBB0_560
	s_and_b64 vcc, exec, s[14:15]
	s_cbranch_vccz .LBB0_563
	s_barrier

; #define PG8_STAGE(bufoff, gbase, voff) do { _Pragma("unroll") for (int _i = 0; _i < 2; ++_i) \
;         __builtin_amdgcn_global_load_lds((const unsigned*)((const char*)(gbase) + (voff)[_i]), (LAS unsigned*)(lds + (bufoff) + ldsw + _i * 8192), 16, 0, 0); } while (0)
; #define PG8_LDA(dst, b, h) do { _Pragma("unroll") for (int m = 0; m < 4; ++m) _Pragma("unroll") for (int k = 0; k < 2; ++k) dst[m][k] = *(const LAS bf16x8*)(lds + PG8_SA(b, h) + aoff + m * 2048 + k * 1024); } while (0)
; #define PG8_LDB(dst, b, h) do { _Pragma("unroll") for (int n = 0; n < 2; ++n) _Pragma("unroll") for (int k = 0; k < 2; ++k) dst[n][k] = *(const LAS bf16x8*)(lds + PG8_SB(b, h) + boff + n * 2048 + k * 1024); } while (0)
; #define PG8_MMA(ai, bj, At, Bt) do { __builtin_amdgcn_s_setprio(1); _Pragma("unroll") for (int m = 0; m < 4; ++m) _Pragma("unroll") for (int n = 0; n < 2; ++n) _Pragma("unroll") for (int k = 0; k < 2; ++k) \
;         acc[ai][bj][m][n] = __builtin_amdgcn_mfma_f32_16x16x32_bf16(Bt[n][k], At[m][k], acc[ai][bj][m][n], 0, 0, 0); __builtin_amdgcn_s_setprio(0); } while (0)
; #define PG8_WAIT_V(n) asm volatile("s_waitcnt vmcnt(" #n ")" ::: "memory")
; #define PG8_WAIT_L(n) asm volatile("s_waitcnt lgkmcnt(" #n ")" ::: "memory")
; template <class Epi, class Sched, bool ALIGN_EPI = false, bool SP2 = false>
; __device__ __forceinline__ void gemm_phase(LAS unsigned char* lds, const Gemm g, const Sched& S, const Epi& E) {
;     ...
;         for (int t = 0; t < nt; t += 2) {
;             const bool last = (t == nt - 2);
;             const char* a1 = cA + (size_t)(t + 1) * kstep;
;             const char* a2 = last ? nA : cA + (size_t)(t + 2) * kstep; const char* b2 = last ? nB : cB + (size_t)(t + 2) * kstep;
;             const char* a3 = a2 + kstep; const char* b3 = b2 + kstep;
;             if (last && has_next) S.a_ready(nxt);
;             if constexpr (SP2) {
;             PG8_LDB(B0, 0, 0); PG8_LDB(B1, 0, 1); PG8_SCHED; PG8_LDA(At, 0, 0); PG8_STAGE(PG8_SA(1, 1), a1 + hstepA, voffA);
;             PG8_WAIT_V(8); PG8_WAIT_L(0); PG8_BAR; PG8_MMA(0, 0, At, B0); PG8_MMA(0, 1, At, B1); PG8_BAR; PG8_SCHED;
;             PG8_LDA(At, 0, 1); PG8_STAGE(PG8_SB(0, 0), b2, voffB); PG8_STAGE(PG8_SB(0, 1), b2 + hstepB, voffB); PG8_STAGE(PG8_SA(0, 0), a2, voffA);
;             PG8_WAIT_V(8); PG8_WAIT_L(0); PG8_BAR; PG8_MMA(1, 0, At, B0); PG8_MMA(1, 1, At, B1); PG8_BAR; PG8_SCHED;
.LBB0_588:
	s_add_u32 s27, s20, s26
	s_addc_u32 s34, s21, 0
	s_add_u32 s30, s27, 0x100
	s_addc_u32 s31, s34, 0
	s_and_b64 s[28:29], s[24:25], exec
	s_cselect_b32 s29, s1, s31
	s_cselect_b32 s28, s0, s30
	s_add_u32 s26, s18, s26
	s_addc_u32 s30, s19, 0
	s_add_u32 s26, s26, 0x100
	s_addc_u32 s30, s30, 0
	s_and_b64 s[24:25], s[24:25], exec
	s_cselect_b32 s31, s17, s30
	s_cselect_b32 s30, s16, s26
	s_add_u32 s36, s27, 0x18080
	ds_read_b128 v[148:151], v142
	ds_read_b128 v[154:157], v142 offset:1024
	ds_read_b128 v[158:161], v142 offset:2048
	ds_read_b128 v[162:165], v142 offset:3072
	ds_read_b128 v[166:169], v143
	ds_read_b128 v[170:173], v143 offset:1024
	ds_read_b128 v[174:177], v143 offset:2048
	ds_read_b128 v[178:181], v143 offset:3072
	s_addc_u32 s37, s34, 0
	s_add_i32 s77, s56, s44
	s_add_i32 m0, s45, 0xc000
	s_add_i32 s78, s45, 0xe000
	s_add_i32 s72, s77, 0x2000
	s_add_u32 s34, s30, 0x18000
	s_addc_u32 s35, s31, 0
	s_add_i32 s76, s57, s44
	s_add_i32 s73, s76, 0x2000
	s_add_u32 s26, s28, 0x18000
	s_addc_u32 s27, s29, 0
	s_add_i32 s71, s59, s44
	s_add_i32 s67, s71, 0x2000
	s_add_u32 s24, s30, 0x18080
	s_addc_u32 s25, s31, 0
	s_add_i32 s70, s60, s44
	s_add_i32 s66, s70, 0x2000
	v_lshl_add_u64 v[214:215], s[36:37], 0, v[130:131]
	ds_read_b128 v[182:185], v144
	ds_read_b128 v[186:189], v144 offset:1024
	ds_read_b128 v[190:193], v144 offset:2048
	ds_read_b128 v[194:197], v144 offset:3072
	ds_read_b128 v[198:201], v144 offset:4096
	ds_read_b128 v[202:205], v144 offset:5120
	ds_read_b128 v[206:209], v144 offset:6144
	ds_read_b128 v[210:213], v144 offset:7168
	global_load_lds_dwordx4 v[214:215], off
	v_lshl_add_u64 v[214:215], s[36:37], 0, v[134:135]
	s_mov_b32 m0, s78
	s_nop 0
	global_load_lds_dwordx4 v[214:215], off
	s_waitcnt vmcnt(8) lgkmcnt(0)
	s_setprio 1
	s_barrier
	v_mfma_f32_16x16x32_bf16 v[126:129], v[148:151], v[182:185], v[126:129]
	v_mfma_f32_16x16x32_bf16 v[122:125], v[158:161], v[182:185], v[122:125]
	v_mfma_f32_16x16x32_bf16 v[118:121], v[148:151], v[190:193], v[118:121]
	v_mfma_f32_16x16x32_bf16 v[110:113], v[158:161], v[190:193], v[110:113]
	v_mfma_f32_16x16x32_bf16 v[102:105], v[148:151], v[198:201], v[102:105]
	v_mfma_f32_16x16x32_bf16 v[94:97], v[158:161], v[198:201], v[94:97]
	v_mfma_f32_16x16x32_bf16 v[86:89], v[148:151], v[206:209], v[86:89]
	v_mfma_f32_16x16x32_bf16 v[78:81], v[158:161], v[206:209], v[78:81]
	v_mfma_f32_16x16x32_bf16 v[126:129], v[154:157], v[186:189], v[126:129]
	v_mfma_f32_16x16x32_bf16 v[122:125], v[162:165], v[186:189], v[122:125]
	v_mfma_f32_16x16x32_bf16 v[118:121], v[154:157], v[194:197], v[118:121]
	v_mfma_f32_16x16x32_bf16 v[110:113], v[162:165], v[194:197], v[110:113]
	v_mfma_f32_16x16x32_bf16 v[102:105], v[154:157], v[202:205], v[102:105]
	v_mfma_f32_16x16x32_bf16 v[94:97], v[162:165], v[202:205], v[94:97]
	v_mfma_f32_16x16x32_bf16 v[86:89], v[154:157], v[210:213], v[86:89]
	v_mfma_f32_16x16x32_bf16 v[78:81], v[162:165], v[210:213], v[78:81]
	s_setprio 0
	s_setprio 1
	v_mfma_f32_16x16x32_bf16 v[114:117], v[166:169], v[182:185], v[114:117]
	v_mfma_f32_16x16x32_bf16 v[106:109], v[174:177], v[182:185], v[106:109]
	v_mfma_f32_16x16x32_bf16 v[98:101], v[166:169], v[190:193], v[98:101]
	v_mfma_f32_16x16x32_bf16 v[90:93], v[174:177], v[190:193], v[90:93]
	v_mfma_f32_16x16x32_bf16 v[82:85], v[166:169], v[198:201], v[82:85]
	v_mfma_f32_16x16x32_bf16 v[74:77], v[174:177], v[198:201], v[74:77]
	v_mfma_f32_16x16x32_bf16 v[70:73], v[166:169], v[206:209], v[70:73]
	v_mfma_f32_16x16x32_bf16 v[66:69], v[174:177], v[206:209], v[66:69]
	v_mfma_f32_16x16x32_bf16 v[114:117], v[170:173], v[186:189], v[114:117]
	v_mfma_f32_16x16x32_bf16 v[106:109], v[178:181], v[186:189], v[106:109]
	v_mfma_f32_16x16x32_bf16 v[98:101], v[170:173], v[194:197], v[98:101]
	v_mfma_f32_16x16x32_bf16 v[90:93], v[178:181], v[194:197], v[90:93]
	v_mfma_f32_16x16x32_bf16 v[82:85], v[170:173], v[202:205], v[82:85]
	v_mfma_f32_16x16x32_bf16 v[74:77], v[178:181], v[202:205], v[74:77]
	v_mfma_f32_16x16x32_bf16 v[70:73], v[170:173], v[210:213], v[70:73]
	v_mfma_f32_16x16x32_bf16 v[66:69], v[178:181], v[210:213], v[66:69]
	s_setprio 0
	s_barrier
	s_mov_b32 m0, s77
	v_lshl_add_u64 v[214:215], s[30:31], 0, v[132:133]
	ds_read_b128 v[182:185], v144 offset:16384
	ds_read_b128 v[186:189], v144 offset:17408
	ds_read_b128 v[190:193], v144 offset:18432
	ds_read_b128 v[194:197], v144 offset:19456
	ds_read_b128 v[198:201], v144 offset:20480
	ds_read_b128 v[202:205], v144 offset:21504
	ds_read_b128 v[206:209], v144 offset:22528
	ds_read_b128 v[210:213], v144 offset:23552
	global_load_lds_dwordx4 v[214:215], off
	v_lshl_add_u64 v[216:217], s[30:31], 0, v[136:137]
	s_mov_b32 m0, s72
	v_lshl_add_u64 v[218:219], s[34:35], 0, v[132:133]
	global_load_lds_dwordx4 v[216:217], off
	s_mov_b32 m0, s76
	v_lshl_add_u64 v[220:221], s[28:29], 0, v[134:135]
	global_load_lds_dwordx4 v[218:219], off
	v_lshl_add_u64 v[218:219], s[34:35], 0, v[136:137]
	s_mov_b32 m0, s73
	s_nop 0
	global_load_lds_dwordx4 v[218:219], off
	v_lshl_add_u64 v[218:219], s[28:29], 0, v[130:131]
	s_mov_b32 m0, s45
	s_nop 0
	global_load_lds_dwordx4 v[218:219], off
	s_mov_b32 m0, s46
	s_nop 0
	global_load_lds_dwordx4 v[220:221], off
	s_waitcnt vmcnt(8) lgkmcnt(0)
	s_setprio 1
	s_barrier
; #define PG8_STAGE(bufoff, gbase, voff) do { _Pragma("unroll") for (int _i = 0; _i < 2; ++_i) \
;         __builtin_amdgcn_global_load_lds((const unsigned*)((const char*)(gbase) + (voff)[_i]), (LAS unsigned*)(lds + (bufoff) + ldsw + _i * 8192), 16, 0, 0); } while (0)
; #define PG8_LDA(dst, b, h) do { _Pragma("unroll") for (int m = 0; m < 4; ++m) _Pragma("unroll") for (int k = 0; k < 2; ++k) dst[m][k] = *(const LAS bf16x8*)(lds + PG8_SA(b, h) + aoff + m * 2048 + k * 1024); } while (0)
; #define PG8_LDB(dst, b, h) do { _Pragma("unroll") for (int n = 0; n < 2; ++n) _Pragma("unroll") for (int k = 0; k < 2; ++k) dst[n][k] = *(const LAS bf16x8*)(lds + PG8_SB(b, h) + boff + n * 2048 + k * 1024); } while (0)
; #define PG8_MMA(ai, bj, At, Bt) do { __builtin_amdgcn_s_setprio(1); _Pragma("unroll") for (int m = 0; m < 4; ++m) _Pragma("unroll") for (int n = 0; n < 2; ++n) _Pragma("unroll") for (int k = 0; k < 2; ++k) \
;         acc[ai][bj][m][n] = __builtin_amdgcn_mfma_f32_16x16x32_bf16(Bt[n][k], At[m][k], acc[ai][bj][m][n], 0, 0, 0); __builtin_amdgcn_s_setprio(0); } while (0)
; #define PG8_WAIT_V(n) asm volatile("s_waitcnt vmcnt(" #n ")" ::: "memory")
; #define PG8_WAIT_L(n) asm volatile("s_waitcnt lgkmcnt(" #n ")" ::: "memory")
; #define PG8_BAR __builtin_amdgcn_s_barrier()
; #define PG8_SCHED __builtin_amdgcn_sched_barrier(0)
; template <class Epi, class Sched, bool ALIGN_EPI = false, bool SP2 = false>
; __device__ __forceinline__ void gemm_phase(LAS unsigned char* lds, const Gemm g, const Sched& S, const Epi& E) {
;     ...
;             PG8_WAIT_V(8); PG8_WAIT_L(0); PG8_BAR; PG8_MMA(1, 0, At, B0); PG8_MMA(1, 1, At, B1); PG8_BAR; PG8_SCHED;
;             PG8_LDB(B0, 1, 0); PG8_LDB(B1, 1, 1); PG8_SCHED; PG8_LDA(At, 1, 0); PG8_STAGE(PG8_SA(0, 1), a2 + hstepA, voffA);
;             PG8_WAIT_V(8); PG8_WAIT_L(0); PG8_BAR; PG8_MMA(0, 0, At, B0); PG8_MMA(0, 1, At, B1); PG8_BAR; PG8_SCHED;
	v_mfma_f32_16x16x32_bf16 v[62:65], v[148:151], v[182:185], v[62:65]
	v_mfma_f32_16x16x32_bf16 v[58:61], v[158:161], v[182:185], v[58:61]
	v_mfma_f32_16x16x32_bf16 v[54:57], v[148:151], v[190:193], v[54:57]
	v_mfma_f32_16x16x32_bf16 v[46:49], v[158:161], v[190:193], v[46:49]
	v_mfma_f32_16x16x32_bf16 v[38:41], v[148:151], v[198:201], v[38:41]
	v_mfma_f32_16x16x32_bf16 v[30:33], v[158:161], v[198:201], v[30:33]
	v_mfma_f32_16x16x32_bf16 v[22:25], v[148:151], v[206:209], v[22:25]
	v_mfma_f32_16x16x32_bf16 v[14:17], v[158:161], v[206:209], v[14:17]
	v_mfma_f32_16x16x32_bf16 v[62:65], v[154:157], v[186:189], v[62:65]
	v_mfma_f32_16x16x32_bf16 v[58:61], v[162:165], v[186:189], v[58:61]
	v_mfma_f32_16x16x32_bf16 v[54:57], v[154:157], v[194:197], v[54:57]
	v_mfma_f32_16x16x32_bf16 v[46:49], v[162:165], v[194:197], v[46:49]
	v_mfma_f32_16x16x32_bf16 v[38:41], v[154:157], v[202:205], v[38:41]
	v_mfma_f32_16x16x32_bf16 v[30:33], v[162:165], v[202:205], v[30:33]
	v_mfma_f32_16x16x32_bf16 v[22:25], v[154:157], v[210:213], v[22:25]
	v_mfma_f32_16x16x32_bf16 v[14:17], v[162:165], v[210:213], v[14:17]
	s_setprio 0
	s_setprio 1
	v_mfma_f32_16x16x32_bf16 v[50:53], v[166:169], v[182:185], v[50:53]
	v_mfma_f32_16x16x32_bf16 v[42:45], v[174:177], v[182:185], v[42:45]
	v_mfma_f32_16x16x32_bf16 v[34:37], v[166:169], v[190:193], v[34:37]
	v_mfma_f32_16x16x32_bf16 v[26:29], v[174:177], v[190:193], v[26:29]
	v_mfma_f32_16x16x32_bf16 v[18:21], v[166:169], v[198:201], v[18:21]
	v_mfma_f32_16x16x32_bf16 v[10:13], v[174:177], v[198:201], v[10:13]
	v_mfma_f32_16x16x32_bf16 v[6:9], v[166:169], v[206:209], v[6:9]
	v_mfma_f32_16x16x32_bf16 v[2:5], v[174:177], v[206:209], v[2:5]
	v_mfma_f32_16x16x32_bf16 v[50:53], v[170:173], v[186:189], v[50:53]
	v_mfma_f32_16x16x32_bf16 v[42:45], v[178:181], v[186:189], v[42:45]
	v_mfma_f32_16x16x32_bf16 v[34:37], v[170:173], v[194:197], v[34:37]
	v_mfma_f32_16x16x32_bf16 v[26:29], v[178:181], v[194:197], v[26:29]
	v_mfma_f32_16x16x32_bf16 v[18:21], v[170:173], v[202:205], v[18:21]
	v_mfma_f32_16x16x32_bf16 v[10:13], v[178:181], v[202:205], v[10:13]
	v_mfma_f32_16x16x32_bf16 v[6:9], v[170:173], v[210:213], v[6:9]
	v_mfma_f32_16x16x32_bf16 v[2:5], v[178:181], v[210:213], v[2:5]
	s_setprio 0
	s_barrier
	ds_read_b128 v[148:151], v146
	ds_read_b128 v[154:157], v146 offset:1024
	ds_read_b128 v[158:161], v146 offset:2048
	ds_read_b128 v[162:165], v146 offset:3072
	ds_read_b128 v[166:169], v147
	ds_read_b128 v[170:173], v147 offset:1024
	ds_read_b128 v[174:177], v147 offset:2048
	ds_read_b128 v[178:181], v147 offset:3072
	s_mov_b32 m0, s47
	v_lshl_add_u64 v[222:223], s[26:27], 0, v[130:131]
	ds_read_b128 v[182:185], v144 offset:32768
	ds_read_b128 v[186:189], v144 offset:33792
	ds_read_b128 v[190:193], v144 offset:34816
	ds_read_b128 v[194:197], v144 offset:35840
	ds_read_b128 v[198:201], v144 offset:36864
	ds_read_b128 v[202:205], v144 offset:37888
	ds_read_b128 v[206:209], v144 offset:38912
	ds_read_b128 v[210:213], v144 offset:39936
	global_load_lds_dwordx4 v[222:223], off
	v_lshl_add_u64 v[222:223], s[26:27], 0, v[134:135]
	s_mov_b32 m0, s50
	s_nop 0
	global_load_lds_dwordx4 v[222:223], off
	s_waitcnt vmcnt(8) lgkmcnt(0)
	s_setprio 1
	s_barrier
	v_mfma_f32_16x16x32_bf16 v[126:129], v[148:151], v[182:185], v[126:129]
	v_mfma_f32_16x16x32_bf16 v[122:125], v[158:161], v[182:185], v[122:125]
	v_mfma_f32_16x16x32_bf16 v[118:121], v[148:151], v[190:193], v[118:121]
	v_mfma_f32_16x16x32_bf16 v[110:113], v[158:161], v[190:193], v[110:113]
	v_mfma_f32_16x16x32_bf16 v[102:105], v[148:151], v[198:201], v[102:105]
	v_mfma_f32_16x16x32_bf16 v[94:97], v[158:161], v[198:201], v[94:97]
	v_mfma_f32_16x16x32_bf16 v[86:89], v[148:151], v[206:209], v[86:89]
	v_mfma_f32_16x16x32_bf16 v[78:81], v[158:161], v[206:209], v[78:81]
	v_mfma_f32_16x16x32_bf16 v[126:129], v[154:157], v[186:189], v[126:129]
	v_mfma_f32_16x16x32_bf16 v[122:125], v[162:165], v[186:189], v[122:125]
	v_mfma_f32_16x16x32_bf16 v[118:121], v[154:157], v[194:197], v[118:121]
	v_mfma_f32_16x16x32_bf16 v[110:113], v[162:165], v[194:197], v[110:113]
	v_mfma_f32_16x16x32_bf16 v[102:105], v[154:157], v[202:205], v[102:105]
	v_mfma_f32_16x16x32_bf16 v[94:97], v[162:165], v[202:205], v[94:97]
	v_mfma_f32_16x16x32_bf16 v[86:89], v[154:157], v[210:213], v[86:89]
	v_mfma_f32_16x16x32_bf16 v[78:81], v[162:165], v[210:213], v[78:81]
	s_setprio 0
	s_setprio 1
	v_mfma_f32_16x16x32_bf16 v[114:117], v[166:169], v[182:185], v[114:117]
	v_mfma_f32_16x16x32_bf16 v[106:109], v[174:177], v[182:185], v[106:109]
	v_mfma_f32_16x16x32_bf16 v[98:101], v[166:169], v[190:193], v[98:101]
	v_mfma_f32_16x16x32_bf16 v[90:93], v[174:177], v[190:193], v[90:93]
	v_mfma_f32_16x16x32_bf16 v[82:85], v[166:169], v[198:201], v[82:85]
	v_mfma_f32_16x16x32_bf16 v[74:77], v[174:177], v[198:201], v[74:77]
	v_mfma_f32_16x16x32_bf16 v[70:73], v[166:169], v[206:209], v[70:73]
	v_mfma_f32_16x16x32_bf16 v[66:69], v[174:177], v[206:209], v[66:69]
	v_mfma_f32_16x16x32_bf16 v[114:117], v[170:173], v[186:189], v[114:117]
	v_mfma_f32_16x16x32_bf16 v[106:109], v[178:181], v[186:189], v[106:109]
	v_mfma_f32_16x16x32_bf16 v[98:101], v[170:173], v[194:197], v[98:101]
	v_mfma_f32_16x16x32_bf16 v[90:93], v[178:181], v[194:197], v[90:93]
	v_mfma_f32_16x16x32_bf16 v[82:85], v[170:173], v[202:205], v[82:85]
	v_mfma_f32_16x16x32_bf16 v[74:77], v[178:181], v[202:205], v[74:77]
	v_mfma_f32_16x16x32_bf16 v[70:73], v[170:173], v[210:213], v[70:73]
	v_mfma_f32_16x16x32_bf16 v[66:69], v[178:181], v[210:213], v[66:69]
	s_setprio 0
	s_barrier
; #define PG8_STAGE(bufoff, gbase, voff) do { _Pragma("unroll") for (int _i = 0; _i < 2; ++_i) \
;         __builtin_amdgcn_global_load_lds((const unsigned*)((const char*)(gbase) + (voff)[_i]), (LAS unsigned*)(lds + (bufoff) + ldsw + _i * 8192), 16, 0, 0); } while (0)
; #define PG8_LDA(dst, b, h) do { _Pragma("unroll") for (int m = 0; m < 4; ++m) _Pragma("unroll") for (int k = 0; k < 2; ++k) dst[m][k] = *(const LAS bf16x8*)(lds + PG8_SA(b, h) + aoff + m * 2048 + k * 1024); } while (0)
; #define PG8_MMA(ai, bj, At, Bt) do { __builtin_amdgcn_s_setprio(1); _Pragma("unroll") for (int m = 0; m < 4; ++m) _Pragma("unroll") for (int n = 0; n < 2; ++n) _Pragma("unroll") for (int k = 0; k < 2; ++k) \
;         acc[ai][bj][m][n] = __builtin_amdgcn_mfma_f32_16x16x32_bf16(Bt[n][k], At[m][k], acc[ai][bj][m][n], 0, 0, 0); __builtin_amdgcn_s_setprio(0); } while (0)
; #define PG8_WAIT_V(n) asm volatile("s_waitcnt vmcnt(" #n ")" ::: "memory")
; #define PG8_WAIT_L(n) asm volatile("s_waitcnt lgkmcnt(" #n ")" ::: "memory")
; #define PG8_BAR __builtin_amdgcn_s_barrier()
; #define PG8_SCHED __builtin_amdgcn_sched_barrier(0)
; template <class Epi, class Sched, bool ALIGN_EPI = false, bool SP2 = false>
; __device__ __forceinline__ void gemm_phase(LAS unsigned char* lds, const Gemm g, const Sched& S, const Epi& E) {
;     ...
;             PG8_LDA(At, 1, 1); PG8_STAGE(PG8_SB(1, 0), b3, voffB); PG8_STAGE(PG8_SB(1, 1), b3 + hstepB, voffB); PG8_STAGE(PG8_SA(1, 0), a3, voffA);
;             PG8_WAIT_V(8); PG8_WAIT_L(0); PG8_BAR; PG8_MMA(1, 0, At, B0); PG8_MMA(1, 1, At, B1); PG8_BAR; PG8_SCHED;
;     ...
;         if constexpr (ALIGN_EPI) { if (wr == 0) PG8_BAR; }
	s_mov_b32 m0, s71
	v_lshl_add_u64 v[214:215], v[214:215], 0, s[12:13]
	ds_read_b128 v[182:185], v144 offset:49152
	ds_read_b128 v[186:189], v144 offset:50176
	ds_read_b128 v[190:193], v144 offset:51200
	ds_read_b128 v[194:197], v144 offset:52224
	ds_read_b128 v[198:201], v144 offset:53248
	ds_read_b128 v[202:205], v144 offset:54272
	ds_read_b128 v[206:209], v144 offset:55296
	ds_read_b128 v[210:213], v144 offset:56320
	global_load_lds_dwordx4 v[214:215], off
	v_lshl_add_u64 v[214:215], v[216:217], 0, s[12:13]
	s_mov_b32 m0, s67
	s_nop 0
	global_load_lds_dwordx4 v[214:215], off
	v_lshl_add_u64 v[214:215], s[24:25], 0, v[132:133]
	s_mov_b32 m0, s70
	s_nop 0
	global_load_lds_dwordx4 v[214:215], off
	v_lshl_add_u64 v[214:215], s[24:25], 0, v[136:137]
	s_mov_b32 m0, s66
	s_nop 0
	global_load_lds_dwordx4 v[214:215], off
	v_lshl_add_u64 v[214:215], v[218:219], 0, s[12:13]
	s_mov_b32 m0, s51
	s_nop 0
	global_load_lds_dwordx4 v[214:215], off
	v_lshl_add_u64 v[214:215], v[220:221], 0, s[12:13]
	s_mov_b32 m0, s52
	s_nop 0
	global_load_lds_dwordx4 v[214:215], off
	s_waitcnt vmcnt(8) lgkmcnt(0)
	s_setprio 1
	s_barrier
	v_mfma_f32_16x16x32_bf16 v[62:65], v[148:151], v[182:185], v[62:65]
	v_mfma_f32_16x16x32_bf16 v[58:61], v[158:161], v[182:185], v[58:61]
	v_mfma_f32_16x16x32_bf16 v[54:57], v[148:151], v[190:193], v[54:57]
	v_mfma_f32_16x16x32_bf16 v[46:49], v[158:161], v[190:193], v[46:49]
	v_mfma_f32_16x16x32_bf16 v[38:41], v[148:151], v[198:201], v[38:41]
	v_mfma_f32_16x16x32_bf16 v[30:33], v[158:161], v[198:201], v[30:33]
	v_mfma_f32_16x16x32_bf16 v[22:25], v[148:151], v[206:209], v[22:25]
	v_mfma_f32_16x16x32_bf16 v[14:17], v[158:161], v[206:209], v[14:17]
	v_mfma_f32_16x16x32_bf16 v[62:65], v[154:157], v[186:189], v[62:65]
	v_mfma_f32_16x16x32_bf16 v[58:61], v[162:165], v[186:189], v[58:61]
	v_mfma_f32_16x16x32_bf16 v[54:57], v[154:157], v[194:197], v[54:57]
	v_mfma_f32_16x16x32_bf16 v[46:49], v[162:165], v[194:197], v[46:49]
	v_mfma_f32_16x16x32_bf16 v[38:41], v[154:157], v[202:205], v[38:41]
	v_mfma_f32_16x16x32_bf16 v[30:33], v[162:165], v[202:205], v[30:33]
	v_mfma_f32_16x16x32_bf16 v[22:25], v[154:157], v[210:213], v[22:25]
	v_mfma_f32_16x16x32_bf16 v[14:17], v[162:165], v[210:213], v[14:17]
	s_setprio 0
	s_setprio 1
	v_mfma_f32_16x16x32_bf16 v[50:53], v[166:169], v[182:185], v[50:53]
	v_mfma_f32_16x16x32_bf16 v[42:45], v[174:177], v[182:185], v[42:45]
	v_mfma_f32_16x16x32_bf16 v[34:37], v[166:169], v[190:193], v[34:37]
	v_mfma_f32_16x16x32_bf16 v[26:29], v[174:177], v[190:193], v[26:29]
	v_mfma_f32_16x16x32_bf16 v[18:21], v[166:169], v[198:201], v[18:21]
	v_mfma_f32_16x16x32_bf16 v[10:13], v[174:177], v[198:201], v[10:13]
	v_mfma_f32_16x16x32_bf16 v[6:9], v[166:169], v[206:209], v[6:9]
	v_mfma_f32_16x16x32_bf16 v[2:5], v[174:177], v[206:209], v[2:5]
	v_mfma_f32_16x16x32_bf16 v[50:53], v[170:173], v[186:189], v[50:53]
	v_mfma_f32_16x16x32_bf16 v[42:45], v[178:181], v[186:189], v[42:45]
	v_mfma_f32_16x16x32_bf16 v[34:37], v[170:173], v[194:197], v[34:37]
	v_mfma_f32_16x16x32_bf16 v[26:29], v[178:181], v[194:197], v[26:29]
	v_mfma_f32_16x16x32_bf16 v[18:21], v[170:173], v[202:205], v[18:21]
	v_mfma_f32_16x16x32_bf16 v[10:13], v[178:181], v[202:205], v[10:13]
	v_mfma_f32_16x16x32_bf16 v[6:9], v[170:173], v[210:213], v[6:9]
	v_mfma_f32_16x16x32_bf16 v[2:5], v[178:181], v[210:213], v[2:5]
	s_setprio 0
	s_barrier
	s_movk_i32 s26, 0x100
	s_andn2_b64 vcc, exec, s[22:23]
	s_mov_b64 s[24:25], -1
	s_mov_b64 s[22:23], 0
	s_cbranch_vccz .LBB0_588
	s_and_b64 vcc, exec, s[14:15]
	s_cbranch_vccz .LBB0_591
	s_barrier

; #define PG8_STAGE(bufoff, gbase, voff) do { _Pragma("unroll") for (int _i = 0; _i < 2; ++_i) \
;         __builtin_amdgcn_global_load_lds((const unsigned*)((const char*)(gbase) + (voff)[_i]), (LAS unsigned*)(lds + (bufoff) + ldsw + _i * 8192), 16, 0, 0); } while (0)
; #define PG8_LDA(dst, b, h) do { _Pragma("unroll") for (int m = 0; m < 4; ++m) _Pragma("unroll") for (int k = 0; k < 2; ++k) dst[m][k] = *(const LAS bf16x8*)(lds + PG8_SA(b, h) + aoff + m * 2048 + k * 1024); } while (0)
; #define PG8_LDB(dst, b, h) do { _Pragma("unroll") for (int n = 0; n < 2; ++n) _Pragma("unroll") for (int k = 0; k < 2; ++k) dst[n][k] = *(const LAS bf16x8*)(lds + PG8_SB(b, h) + boff + n * 2048 + k * 1024); } while (0)
; #define PG8_MMA(ai, bj, At, Bt) do { __builtin_amdgcn_s_setprio(1); _Pragma("unroll") for (int m = 0; m < 4; ++m) _Pragma("unroll") for (int n = 0; n < 2; ++n) _Pragma("unroll") for (int k = 0; k < 2; ++k) \
;         acc[ai][bj][m][n] = __builtin_amdgcn_mfma_f32_16x16x32_bf16(Bt[n][k], At[m][k], acc[ai][bj][m][n], 0, 0, 0); __builtin_amdgcn_s_setprio(0); } while (0)
; #define PG8_WAIT_V(n) asm volatile("s_waitcnt vmcnt(" #n ")" ::: "memory")
; #define PG8_WAIT_L(n) asm volatile("s_waitcnt lgkmcnt(" #n ")" ::: "memory")
; template <class Epi, class Sched, bool ALIGN_EPI = false, bool SP2 = false>
; __device__ __forceinline__ void gemm_phase(LAS unsigned char* lds, const Gemm g, const Sched& S, const Epi& E) {
;     ...
;         for (int t = 0; t < nt; t += 2) {
;             const bool last = (t == nt - 2);
;             const char* a1 = cA + (size_t)(t + 1) * kstep;
;             const char* a2 = last ? nA : cA + (size_t)(t + 2) * kstep; const char* b2 = last ? nB : cB + (size_t)(t + 2) * kstep;
;             const char* a3 = a2 + kstep; const char* b3 = b2 + kstep;
;             if (last && has_next) S.a_ready(nxt);
;             if constexpr (SP2) {
;             PG8_LDB(B0, 0, 0); PG8_LDB(B1, 0, 1); PG8_SCHED; PG8_LDA(At, 0, 0); PG8_STAGE(PG8_SA(1, 1), a1 + hstepA, voffA);
;             PG8_WAIT_V(8); PG8_WAIT_L(0); PG8_BAR; PG8_MMA(0, 0, At, B0); PG8_MMA(0, 1, At, B1); PG8_BAR; PG8_SCHED;
;             PG8_LDA(At, 0, 1); PG8_STAGE(PG8_SB(0, 0), b2, voffB); PG8_STAGE(PG8_SB(0, 1), b2 + hstepB, voffB); PG8_STAGE(PG8_SA(0, 0), a2, voffA);
;             PG8_WAIT_V(8); PG8_WAIT_L(0); PG8_BAR; PG8_MMA(1, 0, At, B0); PG8_MMA(1, 1, At, B1); PG8_BAR; PG8_SCHED;
.LBB0_968:
	ds_read_b128 v[120:123], v221
	ds_read_b128 v[124:127], v221 offset:1024
	ds_read_b128 v[136:139], v221 offset:2048
	ds_read_b128 v[140:143], v221 offset:3072
	ds_read_b128 v[144:147], v222
	ds_read_b128 v[148:151], v222 offset:1024
	ds_read_b128 v[170:173], v222 offset:2048
	ds_read_b128 v[174:177], v222 offset:3072
	s_add_u32 s28, s26, 0xfff80080
	s_addc_u32 s29, s27, -1
	s_cmp_eq_u32 s50, 28
	s_cselect_b32 s31, s17, s29
	s_cselect_b32 s30, s23, s28
	s_cselect_b32 s29, s15, s49
	s_cselect_b32 s28, s25, s33
	v_lshl_add_u64 v[210:211], s[26:27], 0, v[162:163]
	s_add_i32 m0, s35, 0xc000
	ds_read_b128 v[178:181], v223
	ds_read_b128 v[182:185], v223 offset:1024
	ds_read_b128 v[186:189], v223 offset:2048
	ds_read_b128 v[190:193], v223 offset:3072
	ds_read_b128 v[194:197], v223 offset:4096
	ds_read_b128 v[198:201], v223 offset:5120
	ds_read_b128 v[202:205], v223 offset:6144
	ds_read_b128 v[206:209], v223 offset:7168
	global_load_lds_dwordx4 v[210:211], off
	v_lshl_add_u64 v[210:211], s[26:27], 0, v[164:165]
	s_add_i32 m0, s35, 0xe000
	s_nop 0
	global_load_lds_dwordx4 v[210:211], off
	s_waitcnt vmcnt(8) lgkmcnt(0)
	s_setprio 1
	s_barrier
	v_mfma_f32_16x16x32_bf16 v[132:135], v[120:123], v[178:181], v[132:135]
	v_mfma_f32_16x16x32_bf16 v[128:131], v[136:139], v[178:181], v[128:131]
	v_mfma_f32_16x16x32_bf16 v[100:103], v[120:123], v[186:189], v[100:103]
	v_mfma_f32_16x16x32_bf16 v[96:99], v[136:139], v[186:189], v[96:99]
	v_mfma_f32_16x16x32_bf16 v[116:119], v[120:123], v[194:197], v[116:119]
	v_mfma_f32_16x16x32_bf16 v[112:115], v[136:139], v[194:197], v[112:115]
	v_mfma_f32_16x16x32_bf16 v[108:111], v[120:123], v[202:205], v[108:111]
	v_mfma_f32_16x16x32_bf16 v[104:107], v[136:139], v[202:205], v[104:107]
	v_mfma_f32_16x16x32_bf16 v[132:135], v[124:127], v[182:185], v[132:135]
	v_mfma_f32_16x16x32_bf16 v[128:131], v[140:143], v[182:185], v[128:131]
	v_mfma_f32_16x16x32_bf16 v[100:103], v[124:127], v[190:193], v[100:103]
	v_mfma_f32_16x16x32_bf16 v[96:99], v[140:143], v[190:193], v[96:99]
	v_mfma_f32_16x16x32_bf16 v[116:119], v[124:127], v[198:201], v[116:119]
	v_mfma_f32_16x16x32_bf16 v[112:115], v[140:143], v[198:201], v[112:115]
	v_mfma_f32_16x16x32_bf16 v[108:111], v[124:127], v[206:209], v[108:111]
	v_mfma_f32_16x16x32_bf16 v[104:107], v[140:143], v[206:209], v[104:107]
	s_setprio 0
	s_setprio 1
	v_mfma_f32_16x16x32_bf16 v[60:63], v[144:147], v[178:181], v[60:63]
	v_mfma_f32_16x16x32_bf16 v[56:59], v[170:173], v[178:181], v[56:59]
	v_mfma_f32_16x16x32_bf16 v[52:55], v[144:147], v[186:189], v[52:55]
	v_mfma_f32_16x16x32_bf16 v[48:51], v[170:173], v[186:189], v[48:51]
	v_mfma_f32_16x16x32_bf16 v[44:47], v[144:147], v[194:197], v[44:47]
	v_mfma_f32_16x16x32_bf16 v[40:43], v[170:173], v[194:197], v[40:43]
	v_mfma_f32_16x16x32_bf16 v[36:39], v[144:147], v[202:205], v[36:39]
	v_mfma_f32_16x16x32_bf16 v[32:35], v[170:173], v[202:205], v[32:35]
	v_mfma_f32_16x16x32_bf16 v[60:63], v[148:151], v[182:185], v[60:63]
	v_mfma_f32_16x16x32_bf16 v[56:59], v[174:177], v[182:185], v[56:59]
	v_mfma_f32_16x16x32_bf16 v[52:55], v[148:151], v[190:193], v[52:55]
	v_mfma_f32_16x16x32_bf16 v[48:51], v[174:177], v[190:193], v[48:51]
	v_mfma_f32_16x16x32_bf16 v[44:47], v[148:151], v[198:201], v[44:47]
	v_mfma_f32_16x16x32_bf16 v[40:43], v[174:177], v[198:201], v[40:43]
	v_mfma_f32_16x16x32_bf16 v[36:39], v[148:151], v[206:209], v[36:39]
	v_mfma_f32_16x16x32_bf16 v[32:35], v[174:177], v[206:209], v[32:35]
	s_setprio 0
	s_barrier
	s_add_i32 s51, s45, s34
	v_lshl_add_u64 v[210:211], s[28:29], 0, v[156:157]
	s_mov_b32 m0, s51
	ds_read_b128 v[178:181], v223 offset:16384
	ds_read_b128 v[182:185], v223 offset:17408
	ds_read_b128 v[186:189], v223 offset:18432
	ds_read_b128 v[190:193], v223 offset:19456
	ds_read_b128 v[194:197], v223 offset:20480
	ds_read_b128 v[198:201], v223 offset:21504
	ds_read_b128 v[202:205], v223 offset:22528
	ds_read_b128 v[206:209], v223 offset:23552
	global_load_lds_dwordx4 v[210:211], off
	s_add_i32 m0, s51, 0x2000
	s_add_u32 s52, s28, 0x80000
	v_lshl_add_u64 v[212:213], s[28:29], 0, v[160:161]
	s_addc_u32 s53, s29, 0
	s_add_i32 s51, s46, s34
	global_load_lds_dwordx4 v[212:213], off
	v_lshl_add_u64 v[214:215], s[52:53], 0, v[156:157]
	s_mov_b32 m0, s51
	v_lshl_add_u64 v[216:217], s[30:31], 0, v[158:159]
	global_load_lds_dwordx4 v[214:215], off
	v_lshl_add_u64 v[214:215], s[52:53], 0, v[160:161]
	s_add_i32 m0, s51, 0x2000
	s_nop 0
	global_load_lds_dwordx4 v[214:215], off
	v_lshl_add_u64 v[214:215], s[30:31], 0, v[154:155]
	s_mov_b32 m0, s35
	s_nop 0
	global_load_lds_dwordx4 v[214:215], off
	s_mov_b32 m0, s36
	s_nop 0
	global_load_lds_dwordx4 v[216:217], off
	s_waitcnt vmcnt(8) lgkmcnt(0)
	s_setprio 1
	s_barrier
; #define PG8_STAGE(bufoff, gbase, voff) do { _Pragma("unroll") for (int _i = 0; _i < 2; ++_i) \
;         __builtin_amdgcn_global_load_lds((const unsigned*)((const char*)(gbase) + (voff)[_i]), (LAS unsigned*)(lds + (bufoff) + ldsw + _i * 8192), 16, 0, 0); } while (0)
; #define PG8_LDA(dst, b, h) do { _Pragma("unroll") for (int m = 0; m < 4; ++m) _Pragma("unroll") for (int k = 0; k < 2; ++k) dst[m][k] = *(const LAS bf16x8*)(lds + PG8_SA(b, h) + aoff + m * 2048 + k * 1024); } while (0)
; #define PG8_LDB(dst, b, h) do { _Pragma("unroll") for (int n = 0; n < 2; ++n) _Pragma("unroll") for (int k = 0; k < 2; ++k) dst[n][k] = *(const LAS bf16x8*)(lds + PG8_SB(b, h) + boff + n * 2048 + k * 1024); } while (0)
; #define PG8_MMA(ai, bj, At, Bt) do { __builtin_amdgcn_s_setprio(1); _Pragma("unroll") for (int m = 0; m < 4; ++m) _Pragma("unroll") for (int n = 0; n < 2; ++n) _Pragma("unroll") for (int k = 0; k < 2; ++k) \
;         acc[ai][bj][m][n] = __builtin_amdgcn_mfma_f32_16x16x32_bf16(Bt[n][k], At[m][k], acc[ai][bj][m][n], 0, 0, 0); __builtin_amdgcn_s_setprio(0); } while (0)
; #define PG8_WAIT_V(n) asm volatile("s_waitcnt vmcnt(" #n ")" ::: "memory")
; #define PG8_WAIT_L(n) asm volatile("s_waitcnt lgkmcnt(" #n ")" ::: "memory")
; #define PG8_BAR __builtin_amdgcn_s_barrier()
; #define PG8_SCHED __builtin_amdgcn_sched_barrier(0)
; template <class Epi, class Sched, bool ALIGN_EPI = false, bool SP2 = false>
; __device__ __forceinline__ void gemm_phase(LAS unsigned char* lds, const Gemm g, const Sched& S, const Epi& E) {
;     ...
;             PG8_WAIT_V(8); PG8_WAIT_L(0); PG8_BAR; PG8_MMA(1, 0, At, B0); PG8_MMA(1, 1, At, B1); PG8_BAR; PG8_SCHED;
;             PG8_LDB(B0, 1, 0); PG8_LDB(B1, 1, 1); PG8_SCHED; PG8_LDA(At, 1, 0); PG8_STAGE(PG8_SA(0, 1), a2 + hstepA, voffA);
;             PG8_WAIT_V(8); PG8_WAIT_L(0); PG8_BAR; PG8_MMA(0, 0, At, B0); PG8_MMA(0, 1, At, B1); PG8_BAR; PG8_SCHED;
	v_mfma_f32_16x16x32_bf16 v[92:95], v[120:123], v[178:181], v[92:95]
	v_mfma_f32_16x16x32_bf16 v[88:91], v[136:139], v[178:181], v[88:91]
	v_mfma_f32_16x16x32_bf16 v[84:87], v[120:123], v[186:189], v[84:87]
	v_mfma_f32_16x16x32_bf16 v[80:83], v[136:139], v[186:189], v[80:83]
	v_mfma_f32_16x16x32_bf16 v[76:79], v[120:123], v[194:197], v[76:79]
	v_mfma_f32_16x16x32_bf16 v[72:75], v[136:139], v[194:197], v[72:75]
	v_mfma_f32_16x16x32_bf16 v[68:71], v[120:123], v[202:205], v[68:71]
	v_mfma_f32_16x16x32_bf16 v[64:67], v[136:139], v[202:205], v[64:67]
	v_mfma_f32_16x16x32_bf16 v[92:95], v[124:127], v[182:185], v[92:95]
	v_mfma_f32_16x16x32_bf16 v[88:91], v[140:143], v[182:185], v[88:91]
	v_mfma_f32_16x16x32_bf16 v[84:87], v[124:127], v[190:193], v[84:87]
	v_mfma_f32_16x16x32_bf16 v[80:83], v[140:143], v[190:193], v[80:83]
	v_mfma_f32_16x16x32_bf16 v[76:79], v[124:127], v[198:201], v[76:79]
	v_mfma_f32_16x16x32_bf16 v[72:75], v[140:143], v[198:201], v[72:75]
	v_mfma_f32_16x16x32_bf16 v[68:71], v[124:127], v[206:209], v[68:71]
	v_mfma_f32_16x16x32_bf16 v[64:67], v[140:143], v[206:209], v[64:67]
	s_setprio 0
	s_setprio 1
	v_mfma_f32_16x16x32_bf16 v[28:31], v[144:147], v[178:181], v[28:31]
	v_mfma_f32_16x16x32_bf16 v[24:27], v[170:173], v[178:181], v[24:27]
	v_mfma_f32_16x16x32_bf16 v[20:23], v[144:147], v[186:189], v[20:23]
	v_mfma_f32_16x16x32_bf16 v[16:19], v[170:173], v[186:189], v[16:19]
	v_mfma_f32_16x16x32_bf16 v[12:15], v[144:147], v[194:197], v[12:15]
	v_mfma_f32_16x16x32_bf16 v[8:11], v[170:173], v[194:197], v[8:11]
	v_mfma_f32_16x16x32_bf16 v[4:7], v[144:147], v[202:205], v[4:7]
	v_mfma_f32_16x16x32_bf16 v[0:3], v[170:173], v[202:205], v[0:3]
	v_mfma_f32_16x16x32_bf16 v[28:31], v[148:151], v[182:185], v[28:31]
	v_mfma_f32_16x16x32_bf16 v[24:27], v[174:177], v[182:185], v[24:27]
	v_mfma_f32_16x16x32_bf16 v[20:23], v[148:151], v[190:193], v[20:23]
	v_mfma_f32_16x16x32_bf16 v[16:19], v[174:177], v[190:193], v[16:19]
	v_mfma_f32_16x16x32_bf16 v[12:15], v[148:151], v[198:201], v[12:15]
	v_mfma_f32_16x16x32_bf16 v[8:11], v[174:177], v[198:201], v[8:11]
	v_mfma_f32_16x16x32_bf16 v[4:7], v[148:151], v[206:209], v[4:7]
	v_mfma_f32_16x16x32_bf16 v[0:3], v[174:177], v[206:209], v[0:3]
	s_setprio 0
	s_barrier
	ds_read_b128 v[120:123], v225
	ds_read_b128 v[124:127], v225 offset:1024
	ds_read_b128 v[136:139], v225 offset:2048
	ds_read_b128 v[140:143], v225 offset:3072
	ds_read_b128 v[144:147], v226
	ds_read_b128 v[148:151], v226 offset:1024
	ds_read_b128 v[170:173], v226 offset:2048
	ds_read_b128 v[174:177], v226 offset:3072
	s_add_u32 s30, s30, 0x80000
	s_addc_u32 s31, s31, 0
	s_mov_b32 m0, s37
	v_lshl_add_u64 v[218:219], s[30:31], 0, v[154:155]
	ds_read_b128 v[178:181], v223 offset:32768
	ds_read_b128 v[182:185], v223 offset:33792
	ds_read_b128 v[186:189], v223 offset:34816
	ds_read_b128 v[190:193], v223 offset:35840
	ds_read_b128 v[194:197], v223 offset:36864
	ds_read_b128 v[198:201], v223 offset:37888
	ds_read_b128 v[202:205], v223 offset:38912
	ds_read_b128 v[206:209], v223 offset:39936
	global_load_lds_dwordx4 v[218:219], off
	v_lshl_add_u64 v[218:219], s[30:31], 0, v[158:159]
	s_mov_b32 m0, s38
	s_nop 0
	global_load_lds_dwordx4 v[218:219], off
	s_waitcnt vmcnt(8) lgkmcnt(0)
	s_setprio 1
	s_barrier
	v_mfma_f32_16x16x32_bf16 v[132:135], v[120:123], v[178:181], v[132:135]
	v_mfma_f32_16x16x32_bf16 v[128:131], v[136:139], v[178:181], v[128:131]
	v_mfma_f32_16x16x32_bf16 v[100:103], v[120:123], v[186:189], v[100:103]
	v_mfma_f32_16x16x32_bf16 v[96:99], v[136:139], v[186:189], v[96:99]
	v_mfma_f32_16x16x32_bf16 v[116:119], v[120:123], v[194:197], v[116:119]
	v_mfma_f32_16x16x32_bf16 v[112:115], v[136:139], v[194:197], v[112:115]
	v_mfma_f32_16x16x32_bf16 v[108:111], v[120:123], v[202:205], v[108:111]
	v_mfma_f32_16x16x32_bf16 v[104:107], v[136:139], v[202:205], v[104:107]
	v_mfma_f32_16x16x32_bf16 v[132:135], v[124:127], v[182:185], v[132:135]
	v_mfma_f32_16x16x32_bf16 v[128:131], v[140:143], v[182:185], v[128:131]
	v_mfma_f32_16x16x32_bf16 v[100:103], v[124:127], v[190:193], v[100:103]
	v_mfma_f32_16x16x32_bf16 v[96:99], v[140:143], v[190:193], v[96:99]
	v_mfma_f32_16x16x32_bf16 v[116:119], v[124:127], v[198:201], v[116:119]
	v_mfma_f32_16x16x32_bf16 v[112:115], v[140:143], v[198:201], v[112:115]
	v_mfma_f32_16x16x32_bf16 v[108:111], v[124:127], v[206:209], v[108:111]
	v_mfma_f32_16x16x32_bf16 v[104:107], v[140:143], v[206:209], v[104:107]
	s_setprio 0
	s_setprio 1
	v_mfma_f32_16x16x32_bf16 v[60:63], v[144:147], v[178:181], v[60:63]
	v_mfma_f32_16x16x32_bf16 v[56:59], v[170:173], v[178:181], v[56:59]
	v_mfma_f32_16x16x32_bf16 v[52:55], v[144:147], v[186:189], v[52:55]
	v_mfma_f32_16x16x32_bf16 v[48:51], v[170:173], v[186:189], v[48:51]
	v_mfma_f32_16x16x32_bf16 v[44:47], v[144:147], v[194:197], v[44:47]
	v_mfma_f32_16x16x32_bf16 v[40:43], v[170:173], v[194:197], v[40:43]
	v_mfma_f32_16x16x32_bf16 v[36:39], v[144:147], v[202:205], v[36:39]
	v_mfma_f32_16x16x32_bf16 v[32:35], v[170:173], v[202:205], v[32:35]
	v_mfma_f32_16x16x32_bf16 v[60:63], v[148:151], v[182:185], v[60:63]
	v_mfma_f32_16x16x32_bf16 v[56:59], v[174:177], v[182:185], v[56:59]
	v_mfma_f32_16x16x32_bf16 v[52:55], v[148:151], v[190:193], v[52:55]
	v_mfma_f32_16x16x32_bf16 v[48:51], v[174:177], v[190:193], v[48:51]
	v_mfma_f32_16x16x32_bf16 v[44:47], v[148:151], v[198:201], v[44:47]
	v_mfma_f32_16x16x32_bf16 v[40:43], v[174:177], v[198:201], v[40:43]
	v_mfma_f32_16x16x32_bf16 v[36:39], v[148:151], v[206:209], v[36:39]
	v_mfma_f32_16x16x32_bf16 v[32:35], v[174:177], v[206:209], v[32:35]
	s_setprio 0
	s_barrier
; #define PG8_STAGE(bufoff, gbase, voff) do { _Pragma("unroll") for (int _i = 0; _i < 2; ++_i) \
;         __builtin_amdgcn_global_load_lds((const unsigned*)((const char*)(gbase) + (voff)[_i]), (LAS unsigned*)(lds + (bufoff) + ldsw + _i * 8192), 16, 0, 0); } while (0)
; #define PG8_LDA(dst, b, h) do { _Pragma("unroll") for (int m = 0; m < 4; ++m) _Pragma("unroll") for (int k = 0; k < 2; ++k) dst[m][k] = *(const LAS bf16x8*)(lds + PG8_SA(b, h) + aoff + m * 2048 + k * 1024); } while (0)
; #define PG8_MMA(ai, bj, At, Bt) do { __builtin_amdgcn_s_setprio(1); _Pragma("unroll") for (int m = 0; m < 4; ++m) _Pragma("unroll") for (int n = 0; n < 2; ++n) _Pragma("unroll") for (int k = 0; k < 2; ++k) \
;         acc[ai][bj][m][n] = __builtin_amdgcn_mfma_f32_16x16x32_bf16(Bt[n][k], At[m][k], acc[ai][bj][m][n], 0, 0, 0); __builtin_amdgcn_s_setprio(0); } while (0)
; #define PG8_WAIT_V(n) asm volatile("s_waitcnt vmcnt(" #n ")" ::: "memory")
; #define PG8_WAIT_L(n) asm volatile("s_waitcnt lgkmcnt(" #n ")" ::: "memory")
; #define PG8_BAR __builtin_amdgcn_s_barrier()
; #define PG8_SCHED __builtin_amdgcn_sched_barrier(0)
; template <class Epi, class Sched, bool ALIGN_EPI = false, bool SP2 = false>
; __device__ __forceinline__ void gemm_phase(LAS unsigned char* lds, const Gemm g, const Sched& S, const Epi& E) {
;     ...
;             PG8_LDA(At, 1, 1); PG8_STAGE(PG8_SB(1, 0), b3, voffB); PG8_STAGE(PG8_SB(1, 1), b3 + hstepB, voffB); PG8_STAGE(PG8_SA(1, 0), a3, voffA);
;             PG8_WAIT_V(8); PG8_WAIT_L(0); PG8_BAR; PG8_MMA(1, 0, At, B0); PG8_MMA(1, 1, At, B1); PG8_BAR; PG8_SCHED;
;     ...
;         if constexpr (ALIGN_EPI) { if (wr == 0) PG8_BAR; }
	s_add_i32 s30, s47, s34
	v_lshl_add_u64 v[210:211], v[210:211], 0, s[10:11]
	s_mov_b32 m0, s30
	ds_read_b128 v[178:181], v223 offset:49152
	ds_read_b128 v[182:185], v223 offset:50176
	ds_read_b128 v[186:189], v223 offset:51200
	ds_read_b128 v[190:193], v223 offset:52224
	ds_read_b128 v[194:197], v223 offset:53248
	ds_read_b128 v[198:201], v223 offset:54272
	ds_read_b128 v[202:205], v223 offset:55296
	ds_read_b128 v[206:209], v223 offset:56320
	global_load_lds_dwordx4 v[210:211], off
	s_add_i32 m0, s30, 0x2000
	s_add_u32 s28, s28, 0x80080
	v_lshl_add_u64 v[210:211], v[212:213], 0, s[10:11]
	s_addc_u32 s29, s29, 0
	s_add_i32 s30, s48, s34
	global_load_lds_dwordx4 v[210:211], off
	v_lshl_add_u64 v[210:211], s[28:29], 0, v[156:157]
	s_mov_b32 m0, s30
	s_nop 0
	global_load_lds_dwordx4 v[210:211], off
	v_lshl_add_u64 v[210:211], s[28:29], 0, v[160:161]
	s_add_i32 m0, s30, 0x2000
	s_nop 0
	global_load_lds_dwordx4 v[210:211], off
	v_lshl_add_u64 v[210:211], v[214:215], 0, s[10:11]
	s_mov_b32 m0, s39
	s_nop 0
	global_load_lds_dwordx4 v[210:211], off
	v_lshl_add_u64 v[210:211], v[216:217], 0, s[10:11]
	s_mov_b32 m0, s40
	s_nop 0
	global_load_lds_dwordx4 v[210:211], off
	s_waitcnt vmcnt(8) lgkmcnt(0)
	s_setprio 1
	s_barrier
	v_mfma_f32_16x16x32_bf16 v[92:95], v[120:123], v[178:181], v[92:95]
	v_mfma_f32_16x16x32_bf16 v[88:91], v[136:139], v[178:181], v[88:91]
	v_mfma_f32_16x16x32_bf16 v[84:87], v[120:123], v[186:189], v[84:87]
	v_mfma_f32_16x16x32_bf16 v[80:83], v[136:139], v[186:189], v[80:83]
	v_mfma_f32_16x16x32_bf16 v[76:79], v[120:123], v[194:197], v[76:79]
	v_mfma_f32_16x16x32_bf16 v[72:75], v[136:139], v[194:197], v[72:75]
	v_mfma_f32_16x16x32_bf16 v[68:71], v[120:123], v[202:205], v[68:71]
	v_mfma_f32_16x16x32_bf16 v[64:67], v[136:139], v[202:205], v[64:67]
	v_mfma_f32_16x16x32_bf16 v[92:95], v[124:127], v[182:185], v[92:95]
	v_mfma_f32_16x16x32_bf16 v[88:91], v[140:143], v[182:185], v[88:91]
	v_mfma_f32_16x16x32_bf16 v[84:87], v[124:127], v[190:193], v[84:87]
	v_mfma_f32_16x16x32_bf16 v[80:83], v[140:143], v[190:193], v[80:83]
	v_mfma_f32_16x16x32_bf16 v[76:79], v[124:127], v[198:201], v[76:79]
	v_mfma_f32_16x16x32_bf16 v[72:75], v[140:143], v[198:201], v[72:75]
	v_mfma_f32_16x16x32_bf16 v[68:71], v[124:127], v[206:209], v[68:71]
	v_mfma_f32_16x16x32_bf16 v[64:67], v[140:143], v[206:209], v[64:67]
	s_setprio 0
	s_setprio 1
	v_mfma_f32_16x16x32_bf16 v[28:31], v[144:147], v[178:181], v[28:31]
	v_mfma_f32_16x16x32_bf16 v[24:27], v[170:173], v[178:181], v[24:27]
	v_mfma_f32_16x16x32_bf16 v[20:23], v[144:147], v[186:189], v[20:23]
	v_mfma_f32_16x16x32_bf16 v[16:19], v[170:173], v[186:189], v[16:19]
	v_mfma_f32_16x16x32_bf16 v[12:15], v[144:147], v[194:197], v[12:15]
	v_mfma_f32_16x16x32_bf16 v[8:11], v[170:173], v[194:197], v[8:11]
	v_mfma_f32_16x16x32_bf16 v[4:7], v[144:147], v[202:205], v[4:7]
	v_mfma_f32_16x16x32_bf16 v[0:3], v[170:173], v[202:205], v[0:3]
	v_mfma_f32_16x16x32_bf16 v[28:31], v[148:151], v[182:185], v[28:31]
	v_mfma_f32_16x16x32_bf16 v[24:27], v[174:177], v[182:185], v[24:27]
	v_mfma_f32_16x16x32_bf16 v[20:23], v[148:151], v[190:193], v[20:23]
	v_mfma_f32_16x16x32_bf16 v[16:19], v[174:177], v[190:193], v[16:19]
	v_mfma_f32_16x16x32_bf16 v[12:15], v[148:151], v[198:201], v[12:15]
	v_mfma_f32_16x16x32_bf16 v[8:11], v[174:177], v[198:201], v[8:11]
	v_mfma_f32_16x16x32_bf16 v[4:7], v[148:151], v[206:209], v[4:7]
	v_mfma_f32_16x16x32_bf16 v[0:3], v[174:177], v[206:209], v[0:3]
	s_add_i32 s50, s50, 2
	s_add_u32 s26, s26, 0x100
	s_addc_u32 s27, s27, 0
	s_add_u32 s33, s33, 0x100
	s_addc_u32 s49, s49, 0
	s_setprio 0
	s_barrier
	s_cmp_gt_u32 s50, 29
	s_cbranch_scc0 .LBB0_968
	s_and_b64 vcc, exec, s[12:13]
	s_cbranch_vccz .LBB0_971
	s_barrier

; #define PG8_STAGE(bufoff, gbase, voff) do { _Pragma("unroll") for (int _i = 0; _i < 2; ++_i) \
;         __builtin_amdgcn_global_load_lds((const unsigned*)((const char*)(gbase) + (voff)[_i]), (LAS unsigned*)(lds + (bufoff) + ldsw + _i * 8192), 16, 0, 0); } while (0)
; #define PG8_LDA(dst, b, h) do { _Pragma("unroll") for (int m = 0; m < 4; ++m) _Pragma("unroll") for (int k = 0; k < 2; ++k) dst[m][k] = *(const LAS bf16x8*)(lds + PG8_SA(b, h) + aoff + m * 2048 + k * 1024); } while (0)
; #define PG8_LDB(dst, b, h) do { _Pragma("unroll") for (int n = 0; n < 2; ++n) _Pragma("unroll") for (int k = 0; k < 2; ++k) dst[n][k] = *(const LAS bf16x8*)(lds + PG8_SB(b, h) + boff + n * 2048 + k * 1024); } while (0)
; #define PG8_MMA(ai, bj, At, Bt) do { __builtin_amdgcn_s_setprio(1); _Pragma("unroll") for (int m = 0; m < 4; ++m) _Pragma("unroll") for (int n = 0; n < 2; ++n) _Pragma("unroll") for (int k = 0; k < 2; ++k) \
;         acc[ai][bj][m][n] = __builtin_amdgcn_mfma_f32_16x16x32_bf16(Bt[n][k], At[m][k], acc[ai][bj][m][n], 0, 0, 0); __builtin_amdgcn_s_setprio(0); } while (0)
; #define PG8_WAIT_V(n) asm volatile("s_waitcnt vmcnt(" #n ")" ::: "memory")
; #define PG8_WAIT_L(n) asm volatile("s_waitcnt lgkmcnt(" #n ")" ::: "memory")
; template <class Epi, class Sched, bool ALIGN_EPI = false, bool SP2 = false>
; __device__ __forceinline__ void gemm_phase(LAS unsigned char* lds, const Gemm g, const Sched& S, const Epi& E) {
;     ...
;         for (int t = 0; t < nt; t += 2) {
;             const bool last = (t == nt - 2);
;             const char* a1 = cA + (size_t)(t + 1) * kstep;
;             const char* a2 = last ? nA : cA + (size_t)(t + 2) * kstep; const char* b2 = last ? nB : cB + (size_t)(t + 2) * kstep;
;             const char* a3 = a2 + kstep; const char* b3 = b2 + kstep;
;             if (last && has_next) S.a_ready(nxt);
;             if constexpr (SP2) {
;             PG8_LDB(B0, 0, 0); PG8_LDB(B1, 0, 1); PG8_SCHED; PG8_LDA(At, 0, 0); PG8_STAGE(PG8_SA(1, 1), a1 + hstepA, voffA);
;             PG8_WAIT_V(8); PG8_WAIT_L(0); PG8_BAR; PG8_MMA(0, 0, At, B0); PG8_MMA(0, 1, At, B1); PG8_BAR; PG8_SCHED;
;             PG8_LDA(At, 0, 1); PG8_STAGE(PG8_SB(0, 0), b2, voffB); PG8_STAGE(PG8_SB(0, 1), b2 + hstepB, voffB); PG8_STAGE(PG8_SA(0, 0), a2, voffA);
;             PG8_WAIT_V(8); PG8_WAIT_L(0); PG8_BAR; PG8_MMA(1, 0, At, B0); PG8_MMA(1, 1, At, B1); PG8_BAR; PG8_SCHED;
.LBB0_1055:
	ds_read_b128 v[80:83], v171
	ds_read_b128 v[88:91], v171 offset:1024
	ds_read_b128 v[92:95], v171 offset:2048
	ds_read_b128 v[96:99], v171 offset:3072
	ds_read_b128 v[162:165], v172
	ds_read_b128 v[166:169], v172 offset:1024
	ds_read_b128 v[178:181], v172 offset:2048
	ds_read_b128 v[182:185], v172 offset:3072
	s_add_u32 s26, s24, 0xfff80080
	s_addc_u32 s27, s25, -1
	s_cmp_eq_u32 s53, 28
	s_cselect_b32 s29, s17, s27
	s_cselect_b32 s28, s49, s26
	s_cselect_b32 s27, s15, s52
	s_cselect_b32 s26, s50, s51
	v_lshl_add_u64 v[218:219], s[24:25], 0, v[154:155]
	s_add_i32 m0, s23, 0xc000
	ds_read_b128 v[186:189], v173
	ds_read_b128 v[190:193], v173 offset:1024
	ds_read_b128 v[194:197], v173 offset:2048
	ds_read_b128 v[198:201], v173 offset:3072
	ds_read_b128 v[202:205], v173 offset:4096
	ds_read_b128 v[206:209], v173 offset:5120
	ds_read_b128 v[210:213], v173 offset:6144
	ds_read_b128 v[214:217], v173 offset:7168
	global_load_lds_dwordx4 v[218:219], off
	v_lshl_add_u64 v[218:219], s[24:25], 0, v[156:157]
	s_add_i32 m0, s23, 0xe000
	s_nop 0
	global_load_lds_dwordx4 v[218:219], off
	s_waitcnt vmcnt(8) lgkmcnt(0)
	s_setprio 1
	s_barrier
	v_mfma_f32_16x16x32_bf16 v[140:143], v[80:83], v[186:189], v[140:143]
	v_mfma_f32_16x16x32_bf16 v[136:139], v[92:95], v[186:189], v[136:139]
	v_mfma_f32_16x16x32_bf16 v[124:127], v[80:83], v[194:197], v[124:127]
	v_mfma_f32_16x16x32_bf16 v[120:123], v[92:95], v[194:197], v[120:123]
	v_mfma_f32_16x16x32_bf16 v[108:111], v[80:83], v[202:205], v[108:111]
	v_mfma_f32_16x16x32_bf16 v[104:107], v[92:95], v[202:205], v[104:107]
	v_mfma_f32_16x16x32_bf16 v[76:79], v[80:83], v[210:213], v[76:79]
	v_mfma_f32_16x16x32_bf16 v[72:75], v[92:95], v[210:213], v[72:75]
	v_mfma_f32_16x16x32_bf16 v[140:143], v[88:91], v[190:193], v[140:143]
	v_mfma_f32_16x16x32_bf16 v[136:139], v[96:99], v[190:193], v[136:139]
	v_mfma_f32_16x16x32_bf16 v[124:127], v[88:91], v[198:201], v[124:127]
	v_mfma_f32_16x16x32_bf16 v[120:123], v[96:99], v[198:201], v[120:123]
	v_mfma_f32_16x16x32_bf16 v[108:111], v[88:91], v[206:209], v[108:111]
	v_mfma_f32_16x16x32_bf16 v[104:107], v[96:99], v[206:209], v[104:107]
	v_mfma_f32_16x16x32_bf16 v[76:79], v[88:91], v[214:217], v[76:79]
	v_mfma_f32_16x16x32_bf16 v[72:75], v[96:99], v[214:217], v[72:75]
	s_setprio 0
	s_setprio 1
	v_mfma_f32_16x16x32_bf16 v[132:135], v[162:165], v[186:189], v[132:135]
	v_mfma_f32_16x16x32_bf16 v[128:131], v[178:181], v[186:189], v[128:131]
	v_mfma_f32_16x16x32_bf16 v[116:119], v[162:165], v[194:197], v[116:119]
	v_mfma_f32_16x16x32_bf16 v[112:115], v[178:181], v[194:197], v[112:115]
	v_mfma_f32_16x16x32_bf16 v[100:103], v[162:165], v[202:205], v[100:103]
	v_mfma_f32_16x16x32_bf16 v[84:87], v[178:181], v[202:205], v[84:87]
	v_mfma_f32_16x16x32_bf16 v[68:71], v[162:165], v[210:213], v[68:71]
	v_mfma_f32_16x16x32_bf16 v[64:67], v[178:181], v[210:213], v[64:67]
	v_mfma_f32_16x16x32_bf16 v[132:135], v[166:169], v[190:193], v[132:135]
	v_mfma_f32_16x16x32_bf16 v[128:131], v[182:185], v[190:193], v[128:131]
	v_mfma_f32_16x16x32_bf16 v[116:119], v[166:169], v[198:201], v[116:119]
	v_mfma_f32_16x16x32_bf16 v[112:115], v[182:185], v[198:201], v[112:115]
	v_mfma_f32_16x16x32_bf16 v[100:103], v[166:169], v[206:209], v[100:103]
	v_mfma_f32_16x16x32_bf16 v[84:87], v[182:185], v[206:209], v[84:87]
	v_mfma_f32_16x16x32_bf16 v[68:71], v[166:169], v[214:217], v[68:71]
	v_mfma_f32_16x16x32_bf16 v[64:67], v[182:185], v[214:217], v[64:67]
	s_setprio 0
	s_barrier
	s_add_i32 s54, s43, s30
	v_lshl_add_u64 v[218:219], s[26:27], 0, v[146:147]
	s_mov_b32 m0, s54
	ds_read_b128 v[186:189], v173 offset:16384
	ds_read_b128 v[190:193], v173 offset:17408
	ds_read_b128 v[194:197], v173 offset:18432
	ds_read_b128 v[198:201], v173 offset:19456
	ds_read_b128 v[202:205], v173 offset:20480
	ds_read_b128 v[206:209], v173 offset:21504
	ds_read_b128 v[210:213], v173 offset:22528
	ds_read_b128 v[214:217], v173 offset:23552
	global_load_lds_dwordx4 v[218:219], off
	s_add_i32 m0, s54, 0x2000
	s_add_u32 s54, s26, 0x80000
	v_lshl_add_u64 v[220:221], s[26:27], 0, v[150:151]
	s_addc_u32 s55, s27, 0
	s_add_i32 s56, s44, s30
	global_load_lds_dwordx4 v[220:221], off
	v_lshl_add_u64 v[222:223], s[54:55], 0, v[146:147]
	s_mov_b32 m0, s56
	v_lshl_add_u64 v[224:225], s[28:29], 0, v[148:149]
	global_load_lds_dwordx4 v[222:223], off
	v_lshl_add_u64 v[222:223], s[54:55], 0, v[150:151]
	s_add_i32 m0, s56, 0x2000
	s_nop 0
	global_load_lds_dwordx4 v[222:223], off
	v_lshl_add_u64 v[222:223], s[28:29], 0, v[144:145]
	s_mov_b32 m0, s23
	s_nop 0
	global_load_lds_dwordx4 v[222:223], off
	s_mov_b32 m0, s35
	s_nop 0
	global_load_lds_dwordx4 v[224:225], off
	s_waitcnt vmcnt(8) lgkmcnt(0)
	s_setprio 1
	s_barrier
; #define PG8_STAGE(bufoff, gbase, voff) do { _Pragma("unroll") for (int _i = 0; _i < 2; ++_i) \
;         __builtin_amdgcn_global_load_lds((const unsigned*)((const char*)(gbase) + (voff)[_i]), (LAS unsigned*)(lds + (bufoff) + ldsw + _i * 8192), 16, 0, 0); } while (0)
; #define PG8_LDA(dst, b, h) do { _Pragma("unroll") for (int m = 0; m < 4; ++m) _Pragma("unroll") for (int k = 0; k < 2; ++k) dst[m][k] = *(const LAS bf16x8*)(lds + PG8_SA(b, h) + aoff + m * 2048 + k * 1024); } while (0)
; #define PG8_LDB(dst, b, h) do { _Pragma("unroll") for (int n = 0; n < 2; ++n) _Pragma("unroll") for (int k = 0; k < 2; ++k) dst[n][k] = *(const LAS bf16x8*)(lds + PG8_SB(b, h) + boff + n * 2048 + k * 1024); } while (0)
; #define PG8_MMA(ai, bj, At, Bt) do { __builtin_amdgcn_s_setprio(1); _Pragma("unroll") for (int m = 0; m < 4; ++m) _Pragma("unroll") for (int n = 0; n < 2; ++n) _Pragma("unroll") for (int k = 0; k < 2; ++k) \
;         acc[ai][bj][m][n] = __builtin_amdgcn_mfma_f32_16x16x32_bf16(Bt[n][k], At[m][k], acc[ai][bj][m][n], 0, 0, 0); __builtin_amdgcn_s_setprio(0); } while (0)
; #define PG8_WAIT_V(n) asm volatile("s_waitcnt vmcnt(" #n ")" ::: "memory")
; #define PG8_WAIT_L(n) asm volatile("s_waitcnt lgkmcnt(" #n ")" ::: "memory")
; #define PG8_BAR __builtin_amdgcn_s_barrier()
; #define PG8_SCHED __builtin_amdgcn_sched_barrier(0)
; template <class Epi, class Sched, bool ALIGN_EPI = false, bool SP2 = false>
; __device__ __forceinline__ void gemm_phase(LAS unsigned char* lds, const Gemm g, const Sched& S, const Epi& E) {
;     ...
;             PG8_WAIT_V(8); PG8_WAIT_L(0); PG8_BAR; PG8_MMA(1, 0, At, B0); PG8_MMA(1, 1, At, B1); PG8_BAR; PG8_SCHED;
;             PG8_LDB(B0, 1, 0); PG8_LDB(B1, 1, 1); PG8_SCHED; PG8_LDA(At, 1, 0); PG8_STAGE(PG8_SA(0, 1), a2 + hstepA, voffA);
;             PG8_WAIT_V(8); PG8_WAIT_L(0); PG8_BAR; PG8_MMA(0, 0, At, B0); PG8_MMA(0, 1, At, B1); PG8_BAR; PG8_SCHED;
	v_mfma_f32_16x16x32_bf16 v[60:63], v[80:83], v[186:189], v[60:63]
	v_mfma_f32_16x16x32_bf16 v[56:59], v[92:95], v[186:189], v[56:59]
	v_mfma_f32_16x16x32_bf16 v[44:47], v[80:83], v[194:197], v[44:47]
	v_mfma_f32_16x16x32_bf16 v[40:43], v[92:95], v[194:197], v[40:43]
	v_mfma_f32_16x16x32_bf16 v[28:31], v[80:83], v[202:205], v[28:31]
	v_mfma_f32_16x16x32_bf16 v[24:27], v[92:95], v[202:205], v[24:27]
	v_mfma_f32_16x16x32_bf16 v[12:15], v[80:83], v[210:213], v[12:15]
	v_mfma_f32_16x16x32_bf16 v[8:11], v[92:95], v[210:213], v[8:11]
	v_mfma_f32_16x16x32_bf16 v[60:63], v[88:91], v[190:193], v[60:63]
	v_mfma_f32_16x16x32_bf16 v[56:59], v[96:99], v[190:193], v[56:59]
	v_mfma_f32_16x16x32_bf16 v[44:47], v[88:91], v[198:201], v[44:47]
	v_mfma_f32_16x16x32_bf16 v[40:43], v[96:99], v[198:201], v[40:43]
	v_mfma_f32_16x16x32_bf16 v[28:31], v[88:91], v[206:209], v[28:31]
	v_mfma_f32_16x16x32_bf16 v[24:27], v[96:99], v[206:209], v[24:27]
	v_mfma_f32_16x16x32_bf16 v[12:15], v[88:91], v[214:217], v[12:15]
	v_mfma_f32_16x16x32_bf16 v[8:11], v[96:99], v[214:217], v[8:11]
	s_setprio 0
	s_setprio 1
	v_mfma_f32_16x16x32_bf16 v[52:55], v[162:165], v[186:189], v[52:55]
	v_mfma_f32_16x16x32_bf16 v[48:51], v[178:181], v[186:189], v[48:51]
	v_mfma_f32_16x16x32_bf16 v[36:39], v[162:165], v[194:197], v[36:39]
	v_mfma_f32_16x16x32_bf16 v[32:35], v[178:181], v[194:197], v[32:35]
	v_mfma_f32_16x16x32_bf16 v[20:23], v[162:165], v[202:205], v[20:23]
	v_mfma_f32_16x16x32_bf16 v[16:19], v[178:181], v[202:205], v[16:19]
	v_mfma_f32_16x16x32_bf16 v[4:7], v[162:165], v[210:213], v[4:7]
	v_mfma_f32_16x16x32_bf16 v[0:3], v[178:181], v[210:213], v[0:3]
	v_mfma_f32_16x16x32_bf16 v[52:55], v[166:169], v[190:193], v[52:55]
	v_mfma_f32_16x16x32_bf16 v[48:51], v[182:185], v[190:193], v[48:51]
	v_mfma_f32_16x16x32_bf16 v[36:39], v[166:169], v[198:201], v[36:39]
	v_mfma_f32_16x16x32_bf16 v[32:35], v[182:185], v[198:201], v[32:35]
	v_mfma_f32_16x16x32_bf16 v[20:23], v[166:169], v[206:209], v[20:23]
	v_mfma_f32_16x16x32_bf16 v[16:19], v[182:185], v[206:209], v[16:19]
	v_mfma_f32_16x16x32_bf16 v[4:7], v[166:169], v[214:217], v[4:7]
	v_mfma_f32_16x16x32_bf16 v[0:3], v[182:185], v[214:217], v[0:3]
	s_setprio 0
	s_barrier
	ds_read_b128 v[80:83], v175
	ds_read_b128 v[88:91], v175 offset:1024
	ds_read_b128 v[92:95], v175 offset:2048
	ds_read_b128 v[96:99], v175 offset:3072
	ds_read_b128 v[162:165], v176
	ds_read_b128 v[166:169], v176 offset:1024
	ds_read_b128 v[178:181], v176 offset:2048
	ds_read_b128 v[182:185], v176 offset:3072
	s_add_u32 s28, s28, 0x80000
	s_addc_u32 s29, s29, 0
	s_mov_b32 m0, s36
	v_lshl_add_u64 v[226:227], s[28:29], 0, v[144:145]
	ds_read_b128 v[186:189], v173 offset:32768
	ds_read_b128 v[190:193], v173 offset:33792
	ds_read_b128 v[194:197], v173 offset:34816
	ds_read_b128 v[198:201], v173 offset:35840
	ds_read_b128 v[202:205], v173 offset:36864
	ds_read_b128 v[206:209], v173 offset:37888
	ds_read_b128 v[210:213], v173 offset:38912
	ds_read_b128 v[214:217], v173 offset:39936
	global_load_lds_dwordx4 v[226:227], off
	v_lshl_add_u64 v[226:227], s[28:29], 0, v[148:149]
	s_mov_b32 m0, s37
	s_nop 0
	global_load_lds_dwordx4 v[226:227], off
	s_waitcnt vmcnt(8) lgkmcnt(0)
	s_setprio 1
	s_barrier
	v_mfma_f32_16x16x32_bf16 v[140:143], v[80:83], v[186:189], v[140:143]
	v_mfma_f32_16x16x32_bf16 v[136:139], v[92:95], v[186:189], v[136:139]
	v_mfma_f32_16x16x32_bf16 v[124:127], v[80:83], v[194:197], v[124:127]
	v_mfma_f32_16x16x32_bf16 v[120:123], v[92:95], v[194:197], v[120:123]
	v_mfma_f32_16x16x32_bf16 v[108:111], v[80:83], v[202:205], v[108:111]
	v_mfma_f32_16x16x32_bf16 v[104:107], v[92:95], v[202:205], v[104:107]
	v_mfma_f32_16x16x32_bf16 v[76:79], v[80:83], v[210:213], v[76:79]
	v_mfma_f32_16x16x32_bf16 v[72:75], v[92:95], v[210:213], v[72:75]
	v_mfma_f32_16x16x32_bf16 v[140:143], v[88:91], v[190:193], v[140:143]
	v_mfma_f32_16x16x32_bf16 v[136:139], v[96:99], v[190:193], v[136:139]
	v_mfma_f32_16x16x32_bf16 v[124:127], v[88:91], v[198:201], v[124:127]
	v_mfma_f32_16x16x32_bf16 v[120:123], v[96:99], v[198:201], v[120:123]
	v_mfma_f32_16x16x32_bf16 v[108:111], v[88:91], v[206:209], v[108:111]
	v_mfma_f32_16x16x32_bf16 v[104:107], v[96:99], v[206:209], v[104:107]
	v_mfma_f32_16x16x32_bf16 v[76:79], v[88:91], v[214:217], v[76:79]
	v_mfma_f32_16x16x32_bf16 v[72:75], v[96:99], v[214:217], v[72:75]
	s_setprio 0
	s_setprio 1
	v_mfma_f32_16x16x32_bf16 v[132:135], v[162:165], v[186:189], v[132:135]
	v_mfma_f32_16x16x32_bf16 v[128:131], v[178:181], v[186:189], v[128:131]
	v_mfma_f32_16x16x32_bf16 v[116:119], v[162:165], v[194:197], v[116:119]
	v_mfma_f32_16x16x32_bf16 v[112:115], v[178:181], v[194:197], v[112:115]
	v_mfma_f32_16x16x32_bf16 v[100:103], v[162:165], v[202:205], v[100:103]
	v_mfma_f32_16x16x32_bf16 v[84:87], v[178:181], v[202:205], v[84:87]
	v_mfma_f32_16x16x32_bf16 v[68:71], v[162:165], v[210:213], v[68:71]
	v_mfma_f32_16x16x32_bf16 v[64:67], v[178:181], v[210:213], v[64:67]
	v_mfma_f32_16x16x32_bf16 v[132:135], v[166:169], v[190:193], v[132:135]
	v_mfma_f32_16x16x32_bf16 v[128:131], v[182:185], v[190:193], v[128:131]
	v_mfma_f32_16x16x32_bf16 v[116:119], v[166:169], v[198:201], v[116:119]
	v_mfma_f32_16x16x32_bf16 v[112:115], v[182:185], v[198:201], v[112:115]
	v_mfma_f32_16x16x32_bf16 v[100:103], v[166:169], v[206:209], v[100:103]
	v_mfma_f32_16x16x32_bf16 v[84:87], v[182:185], v[206:209], v[84:87]
	v_mfma_f32_16x16x32_bf16 v[68:71], v[166:169], v[214:217], v[68:71]
	v_mfma_f32_16x16x32_bf16 v[64:67], v[182:185], v[214:217], v[64:67]
	s_setprio 0
	s_barrier
; #define PG8_STAGE(bufoff, gbase, voff) do { _Pragma("unroll") for (int _i = 0; _i < 2; ++_i) \
;         __builtin_amdgcn_global_load_lds((const unsigned*)((const char*)(gbase) + (voff)[_i]), (LAS unsigned*)(lds + (bufoff) + ldsw + _i * 8192), 16, 0, 0); } while (0)
; #define PG8_LDA(dst, b, h) do { _Pragma("unroll") for (int m = 0; m < 4; ++m) _Pragma("unroll") for (int k = 0; k < 2; ++k) dst[m][k] = *(const LAS bf16x8*)(lds + PG8_SA(b, h) + aoff + m * 2048 + k * 1024); } while (0)
; #define PG8_MMA(ai, bj, At, Bt) do { __builtin_amdgcn_s_setprio(1); _Pragma("unroll") for (int m = 0; m < 4; ++m) _Pragma("unroll") for (int n = 0; n < 2; ++n) _Pragma("unroll") for (int k = 0; k < 2; ++k) \
;         acc[ai][bj][m][n] = __builtin_amdgcn_mfma_f32_16x16x32_bf16(Bt[n][k], At[m][k], acc[ai][bj][m][n], 0, 0, 0); __builtin_amdgcn_s_setprio(0); } while (0)
; #define PG8_WAIT_V(n) asm volatile("s_waitcnt vmcnt(" #n ")" ::: "memory")
; #define PG8_WAIT_L(n) asm volatile("s_waitcnt lgkmcnt(" #n ")" ::: "memory")
; #define PG8_BAR __builtin_amdgcn_s_barrier()
; #define PG8_SCHED __builtin_amdgcn_sched_barrier(0)
; template <class Epi, class Sched, bool ALIGN_EPI = false, bool SP2 = false>
; __device__ __forceinline__ void gemm_phase(LAS unsigned char* lds, const Gemm g, const Sched& S, const Epi& E) {
;     ...
;             PG8_LDA(At, 1, 1); PG8_STAGE(PG8_SB(1, 0), b3, voffB); PG8_STAGE(PG8_SB(1, 1), b3 + hstepB, voffB); PG8_STAGE(PG8_SA(1, 0), a3, voffA);
;             PG8_WAIT_V(8); PG8_WAIT_L(0); PG8_BAR; PG8_MMA(1, 0, At, B0); PG8_MMA(1, 1, At, B1); PG8_BAR; PG8_SCHED;
;     ...
;         if constexpr (ALIGN_EPI) { if (wr == 0) PG8_BAR; }
	s_add_i32 s28, s47, s30
	v_lshl_add_u64 v[218:219], v[218:219], 0, s[8:9]
	s_mov_b32 m0, s28
	ds_read_b128 v[186:189], v173 offset:49152
	ds_read_b128 v[190:193], v173 offset:50176
	ds_read_b128 v[194:197], v173 offset:51200
	ds_read_b128 v[198:201], v173 offset:52224
	ds_read_b128 v[202:205], v173 offset:53248
	ds_read_b128 v[206:209], v173 offset:54272
	ds_read_b128 v[210:213], v173 offset:55296
	ds_read_b128 v[214:217], v173 offset:56320
	global_load_lds_dwordx4 v[218:219], off
	s_add_i32 m0, s28, 0x2000
	s_add_u32 s26, s26, 0x80080
	v_lshl_add_u64 v[218:219], v[220:221], 0, s[8:9]
	s_addc_u32 s27, s27, 0
	s_add_i32 s28, s48, s30
	global_load_lds_dwordx4 v[218:219], off
	v_lshl_add_u64 v[218:219], s[26:27], 0, v[146:147]
	s_mov_b32 m0, s28
	s_nop 0
	global_load_lds_dwordx4 v[218:219], off
	v_lshl_add_u64 v[218:219], s[26:27], 0, v[150:151]
	s_add_i32 m0, s28, 0x2000
	s_nop 0
	global_load_lds_dwordx4 v[218:219], off
	v_lshl_add_u64 v[218:219], v[222:223], 0, s[8:9]
	s_mov_b32 m0, s40
	s_nop 0
	global_load_lds_dwordx4 v[218:219], off
	v_lshl_add_u64 v[218:219], v[224:225], 0, s[8:9]
	s_mov_b32 m0, s41
	s_nop 0
	global_load_lds_dwordx4 v[218:219], off
	s_waitcnt vmcnt(8) lgkmcnt(0)
	s_setprio 1
	s_barrier
	v_mfma_f32_16x16x32_bf16 v[60:63], v[80:83], v[186:189], v[60:63]
	v_mfma_f32_16x16x32_bf16 v[56:59], v[92:95], v[186:189], v[56:59]
	v_mfma_f32_16x16x32_bf16 v[44:47], v[80:83], v[194:197], v[44:47]
	v_mfma_f32_16x16x32_bf16 v[40:43], v[92:95], v[194:197], v[40:43]
	v_mfma_f32_16x16x32_bf16 v[28:31], v[80:83], v[202:205], v[28:31]
	v_mfma_f32_16x16x32_bf16 v[24:27], v[92:95], v[202:205], v[24:27]
	v_mfma_f32_16x16x32_bf16 v[12:15], v[80:83], v[210:213], v[12:15]
	v_mfma_f32_16x16x32_bf16 v[8:11], v[92:95], v[210:213], v[8:11]
	v_mfma_f32_16x16x32_bf16 v[60:63], v[88:91], v[190:193], v[60:63]
	v_mfma_f32_16x16x32_bf16 v[56:59], v[96:99], v[190:193], v[56:59]
	v_mfma_f32_16x16x32_bf16 v[44:47], v[88:91], v[198:201], v[44:47]
	v_mfma_f32_16x16x32_bf16 v[40:43], v[96:99], v[198:201], v[40:43]
	v_mfma_f32_16x16x32_bf16 v[28:31], v[88:91], v[206:209], v[28:31]
	v_mfma_f32_16x16x32_bf16 v[24:27], v[96:99], v[206:209], v[24:27]
	v_mfma_f32_16x16x32_bf16 v[12:15], v[88:91], v[214:217], v[12:15]
	v_mfma_f32_16x16x32_bf16 v[8:11], v[96:99], v[214:217], v[8:11]
	s_setprio 0
	s_setprio 1
	v_mfma_f32_16x16x32_bf16 v[52:55], v[162:165], v[186:189], v[52:55]
	v_mfma_f32_16x16x32_bf16 v[48:51], v[178:181], v[186:189], v[48:51]
	v_mfma_f32_16x16x32_bf16 v[36:39], v[162:165], v[194:197], v[36:39]
	v_mfma_f32_16x16x32_bf16 v[32:35], v[178:181], v[194:197], v[32:35]
	v_mfma_f32_16x16x32_bf16 v[20:23], v[162:165], v[202:205], v[20:23]
	v_mfma_f32_16x16x32_bf16 v[16:19], v[178:181], v[202:205], v[16:19]
	v_mfma_f32_16x16x32_bf16 v[4:7], v[162:165], v[210:213], v[4:7]
	v_mfma_f32_16x16x32_bf16 v[0:3], v[178:181], v[210:213], v[0:3]
	v_mfma_f32_16x16x32_bf16 v[52:55], v[166:169], v[190:193], v[52:55]
	v_mfma_f32_16x16x32_bf16 v[48:51], v[182:185], v[190:193], v[48:51]
	v_mfma_f32_16x16x32_bf16 v[36:39], v[166:169], v[198:201], v[36:39]
	v_mfma_f32_16x16x32_bf16 v[32:35], v[182:185], v[198:201], v[32:35]
	v_mfma_f32_16x16x32_bf16 v[20:23], v[166:169], v[206:209], v[20:23]
	v_mfma_f32_16x16x32_bf16 v[16:19], v[182:185], v[206:209], v[16:19]
	v_mfma_f32_16x16x32_bf16 v[4:7], v[166:169], v[214:217], v[4:7]
	v_mfma_f32_16x16x32_bf16 v[0:3], v[182:185], v[214:217], v[0:3]
	s_add_i32 s53, s53, 2
	s_add_u32 s24, s24, 0x100
	s_addc_u32 s25, s25, 0
	s_add_u32 s51, s51, 0x100
	s_addc_u32 s52, s52, 0
	s_setprio 0
	s_barrier
	s_cmp_gt_u32 s53, 29
	s_cbranch_scc0 .LBB0_1055
	s_and_b64 vcc, exec, s[10:11]
	s_cbranch_vccz .LBB0_1058
	s_barrier

; #define PG8_STAGE(bufoff, gbase, voff) do { _Pragma("unroll") for (int _i = 0; _i < 2; ++_i) \
;         __builtin_amdgcn_global_load_lds((const unsigned*)((const char*)(gbase) + (voff)[_i]), (LAS unsigned*)(lds + (bufoff) + ldsw + _i * 8192), 16, 0, 0); } while (0)
; #define PG8_LDA(dst, b, h) do { _Pragma("unroll") for (int m = 0; m < 4; ++m) _Pragma("unroll") for (int k = 0; k < 2; ++k) dst[m][k] = *(const LAS bf16x8*)(lds + PG8_SA(b, h) + aoff + m * 2048 + k * 1024); } while (0)
; #define PG8_LDB(dst, b, h) do { _Pragma("unroll") for (int n = 0; n < 2; ++n) _Pragma("unroll") for (int k = 0; k < 2; ++k) dst[n][k] = *(const LAS bf16x8*)(lds + PG8_SB(b, h) + boff + n * 2048 + k * 1024); } while (0)
; #define PG8_MMA(ai, bj, At, Bt) do { __builtin_amdgcn_s_setprio(1); _Pragma("unroll") for (int m = 0; m < 4; ++m) _Pragma("unroll") for (int n = 0; n < 2; ++n) _Pragma("unroll") for (int k = 0; k < 2; ++k) \
;         acc[ai][bj][m][n] = __builtin_amdgcn_mfma_f32_16x16x32_bf16(Bt[n][k], At[m][k], acc[ai][bj][m][n], 0, 0, 0); __builtin_amdgcn_s_setprio(0); } while (0)
; #define PG8_WAIT_V(n) asm volatile("s_waitcnt vmcnt(" #n ")" ::: "memory")
; #define PG8_WAIT_L(n) asm volatile("s_waitcnt lgkmcnt(" #n ")" ::: "memory")
; template <class Epi, class Sched, bool ALIGN_EPI = false, bool SP2 = false>
; __device__ __forceinline__ void gemm_phase(LAS unsigned char* lds, const Gemm g, const Sched& S, const Epi& E) {
;     ...
;         for (int t = 0; t < nt; t += 2) {
;             const bool last = (t == nt - 2);
;             const char* a1 = cA + (size_t)(t + 1) * kstep;
;             const char* a2 = last ? nA : cA + (size_t)(t + 2) * kstep; const char* b2 = last ? nB : cB + (size_t)(t + 2) * kstep;
;             const char* a3 = a2 + kstep; const char* b3 = b2 + kstep;
;             if (last && has_next) S.a_ready(nxt);
;             if constexpr (SP2) {
;             PG8_LDB(B0, 0, 0); PG8_LDB(B1, 0, 1); PG8_SCHED; PG8_LDA(At, 0, 0); PG8_STAGE(PG8_SA(1, 1), a1 + hstepA, voffA);
;             PG8_WAIT_V(8); PG8_WAIT_L(0); PG8_BAR; PG8_MMA(0, 0, At, B0); PG8_MMA(0, 1, At, B1); PG8_BAR; PG8_SCHED;
;             PG8_LDA(At, 0, 1); PG8_STAGE(PG8_SB(0, 0), b2, voffB); PG8_STAGE(PG8_SB(0, 1), b2 + hstepB, voffB); PG8_STAGE(PG8_SA(0, 0), a2, voffA);
;             PG8_WAIT_V(8); PG8_WAIT_L(0); PG8_BAR; PG8_MMA(1, 0, At, B0); PG8_MMA(1, 1, At, B1); PG8_BAR; PG8_SCHED;
.LBB0_1138:
	ds_read_b128 v[128:131], v176
	ds_read_b128 v[132:135], v176 offset:1024
	ds_read_b128 v[152:155], v176 offset:2048
	ds_read_b128 v[156:159], v176 offset:3072
	ds_read_b128 v[160:163], v177
	ds_read_b128 v[164:167], v177 offset:1024
	ds_read_b128 v[168:171], v177 offset:2048
	ds_read_b128 v[182:185], v177 offset:3072
	s_add_u32 s22, s20, 0xffea0080
	s_addc_u32 s23, s21, -1
	s_cmpk_eq_i32 s49, 0x54
	s_cselect_b32 s25, s3, s23
	s_cselect_b32 s24, s2, s22
	s_cselect_b32 s23, s19, s48
	s_cselect_b32 s22, s18, s47
	v_lshl_add_u64 v[172:173], s[20:21], 0, v[144:145]
	s_add_i32 m0, s28, 0xc000
	ds_read_b128 v[186:189], v178
	ds_read_b128 v[190:193], v178 offset:1024
	ds_read_b128 v[194:197], v178 offset:2048
	ds_read_b128 v[198:201], v178 offset:3072
	ds_read_b128 v[202:205], v178 offset:4096
	ds_read_b128 v[206:209], v178 offset:5120
	ds_read_b128 v[210:213], v178 offset:6144
	ds_read_b128 v[214:217], v178 offset:7168
	global_load_lds_dwordx4 v[172:173], off
	v_lshl_add_u64 v[172:173], s[20:21], 0, v[146:147]
	s_add_i32 m0, s28, 0xe000
	s_nop 0
	global_load_lds_dwordx4 v[172:173], off
	s_waitcnt vmcnt(8) lgkmcnt(0)
	s_setprio 1
	s_barrier
	v_mfma_f32_16x16x32_bf16 v[124:127], v[128:131], v[186:189], v[124:127]
	v_mfma_f32_16x16x32_bf16 v[120:123], v[152:155], v[186:189], v[120:123]
	v_mfma_f32_16x16x32_bf16 v[116:119], v[128:131], v[194:197], v[116:119]
	v_mfma_f32_16x16x32_bf16 v[112:115], v[152:155], v[194:197], v[112:115]
	v_mfma_f32_16x16x32_bf16 v[108:111], v[128:131], v[202:205], v[108:111]
	v_mfma_f32_16x16x32_bf16 v[104:107], v[152:155], v[202:205], v[104:107]
	v_mfma_f32_16x16x32_bf16 v[100:103], v[128:131], v[210:213], v[100:103]
	v_mfma_f32_16x16x32_bf16 v[96:99], v[152:155], v[210:213], v[96:99]
	v_mfma_f32_16x16x32_bf16 v[124:127], v[132:135], v[190:193], v[124:127]
	v_mfma_f32_16x16x32_bf16 v[120:123], v[156:159], v[190:193], v[120:123]
	v_mfma_f32_16x16x32_bf16 v[116:119], v[132:135], v[198:201], v[116:119]
	v_mfma_f32_16x16x32_bf16 v[112:115], v[156:159], v[198:201], v[112:115]
	v_mfma_f32_16x16x32_bf16 v[108:111], v[132:135], v[206:209], v[108:111]
	v_mfma_f32_16x16x32_bf16 v[104:107], v[156:159], v[206:209], v[104:107]
	v_mfma_f32_16x16x32_bf16 v[100:103], v[132:135], v[214:217], v[100:103]
	v_mfma_f32_16x16x32_bf16 v[96:99], v[156:159], v[214:217], v[96:99]
	s_setprio 0
	s_setprio 1
	v_mfma_f32_16x16x32_bf16 v[68:71], v[160:163], v[186:189], v[68:71]
	v_mfma_f32_16x16x32_bf16 v[60:63], v[168:171], v[186:189], v[60:63]
	v_mfma_f32_16x16x32_bf16 v[52:55], v[160:163], v[194:197], v[52:55]
	v_mfma_f32_16x16x32_bf16 v[48:51], v[168:171], v[194:197], v[48:51]
	v_mfma_f32_16x16x32_bf16 v[44:47], v[160:163], v[202:205], v[44:47]
	v_mfma_f32_16x16x32_bf16 v[40:43], v[168:171], v[202:205], v[40:43]
	v_mfma_f32_16x16x32_bf16 v[36:39], v[160:163], v[210:213], v[36:39]
	v_mfma_f32_16x16x32_bf16 v[32:35], v[168:171], v[210:213], v[32:35]
	v_mfma_f32_16x16x32_bf16 v[68:71], v[164:167], v[190:193], v[68:71]
	v_mfma_f32_16x16x32_bf16 v[60:63], v[182:185], v[190:193], v[60:63]
	v_mfma_f32_16x16x32_bf16 v[52:55], v[164:167], v[198:201], v[52:55]
	v_mfma_f32_16x16x32_bf16 v[48:51], v[182:185], v[198:201], v[48:51]
	v_mfma_f32_16x16x32_bf16 v[44:47], v[164:167], v[206:209], v[44:47]
	v_mfma_f32_16x16x32_bf16 v[40:43], v[182:185], v[206:209], v[40:43]
	v_mfma_f32_16x16x32_bf16 v[36:39], v[164:167], v[214:217], v[36:39]
	v_mfma_f32_16x16x32_bf16 v[32:35], v[182:185], v[214:217], v[32:35]
	s_setprio 0
	s_barrier
	s_add_i32 s50, s40, s27
	v_lshl_add_u64 v[172:173], s[22:23], 0, v[138:139]
	s_mov_b32 m0, s50
	ds_read_b128 v[186:189], v178 offset:16384
	ds_read_b128 v[190:193], v178 offset:17408
	ds_read_b128 v[194:197], v178 offset:18432
	ds_read_b128 v[198:201], v178 offset:19456
	ds_read_b128 v[202:205], v178 offset:20480
	ds_read_b128 v[206:209], v178 offset:21504
	ds_read_b128 v[210:213], v178 offset:22528
	ds_read_b128 v[214:217], v178 offset:23552
	global_load_lds_dwordx4 v[172:173], off
	s_add_i32 m0, s50, 0x2000
	s_add_u32 s50, s22, 0x160000
	v_lshl_add_u64 v[218:219], s[22:23], 0, v[142:143]
	s_addc_u32 s51, s23, 0
	s_add_i32 s52, s41, s27
	global_load_lds_dwordx4 v[218:219], off
	v_lshl_add_u64 v[220:221], s[50:51], 0, v[138:139]
	s_mov_b32 m0, s52
	v_lshl_add_u64 v[222:223], s[24:25], 0, v[140:141]
	global_load_lds_dwordx4 v[220:221], off
	v_lshl_add_u64 v[220:221], s[50:51], 0, v[142:143]
	s_add_i32 m0, s52, 0x2000
	s_nop 0
	global_load_lds_dwordx4 v[220:221], off
	v_lshl_add_u64 v[220:221], s[24:25], 0, v[136:137]
	s_mov_b32 m0, s28
	s_nop 0
	global_load_lds_dwordx4 v[220:221], off
	s_mov_b32 m0, s29
	s_nop 0
	global_load_lds_dwordx4 v[222:223], off
	s_waitcnt vmcnt(8) lgkmcnt(0)
	s_setprio 1
	s_barrier
; #define PG8_STAGE(bufoff, gbase, voff) do { _Pragma("unroll") for (int _i = 0; _i < 2; ++_i) \
;         __builtin_amdgcn_global_load_lds((const unsigned*)((const char*)(gbase) + (voff)[_i]), (LAS unsigned*)(lds + (bufoff) + ldsw + _i * 8192), 16, 0, 0); } while (0)
; #define PG8_LDA(dst, b, h) do { _Pragma("unroll") for (int m = 0; m < 4; ++m) _Pragma("unroll") for (int k = 0; k < 2; ++k) dst[m][k] = *(const LAS bf16x8*)(lds + PG8_SA(b, h) + aoff + m * 2048 + k * 1024); } while (0)
; #define PG8_LDB(dst, b, h) do { _Pragma("unroll") for (int n = 0; n < 2; ++n) _Pragma("unroll") for (int k = 0; k < 2; ++k) dst[n][k] = *(const LAS bf16x8*)(lds + PG8_SB(b, h) + boff + n * 2048 + k * 1024); } while (0)
; #define PG8_MMA(ai, bj, At, Bt) do { __builtin_amdgcn_s_setprio(1); _Pragma("unroll") for (int m = 0; m < 4; ++m) _Pragma("unroll") for (int n = 0; n < 2; ++n) _Pragma("unroll") for (int k = 0; k < 2; ++k) \
;         acc[ai][bj][m][n] = __builtin_amdgcn_mfma_f32_16x16x32_bf16(Bt[n][k], At[m][k], acc[ai][bj][m][n], 0, 0, 0); __builtin_amdgcn_s_setprio(0); } while (0)
; #define PG8_WAIT_V(n) asm volatile("s_waitcnt vmcnt(" #n ")" ::: "memory")
; #define PG8_WAIT_L(n) asm volatile("s_waitcnt lgkmcnt(" #n ")" ::: "memory")
; #define PG8_BAR __builtin_amdgcn_s_barrier()
; #define PG8_SCHED __builtin_amdgcn_sched_barrier(0)
; template <class Epi, class Sched, bool ALIGN_EPI = false, bool SP2 = false>
; __device__ __forceinline__ void gemm_phase(LAS unsigned char* lds, const Gemm g, const Sched& S, const Epi& E) {
;     ...
;             PG8_WAIT_V(8); PG8_WAIT_L(0); PG8_BAR; PG8_MMA(1, 0, At, B0); PG8_MMA(1, 1, At, B1); PG8_BAR; PG8_SCHED;
;             PG8_LDB(B0, 1, 0); PG8_LDB(B1, 1, 1); PG8_SCHED; PG8_LDA(At, 1, 0); PG8_STAGE(PG8_SA(0, 1), a2 + hstepA, voffA);
;             PG8_WAIT_V(8); PG8_WAIT_L(0); PG8_BAR; PG8_MMA(0, 0, At, B0); PG8_MMA(0, 1, At, B1); PG8_BAR; PG8_SCHED;
	v_mfma_f32_16x16x32_bf16 v[92:95], v[128:131], v[186:189], v[92:95]
	v_mfma_f32_16x16x32_bf16 v[88:91], v[152:155], v[186:189], v[88:91]
	v_mfma_f32_16x16x32_bf16 v[84:87], v[128:131], v[194:197], v[84:87]
	v_mfma_f32_16x16x32_bf16 v[80:83], v[152:155], v[194:197], v[80:83]
	v_mfma_f32_16x16x32_bf16 v[76:79], v[128:131], v[202:205], v[76:79]
	v_mfma_f32_16x16x32_bf16 v[72:75], v[152:155], v[202:205], v[72:75]
	v_mfma_f32_16x16x32_bf16 v[64:67], v[128:131], v[210:213], v[64:67]
	v_mfma_f32_16x16x32_bf16 v[56:59], v[152:155], v[210:213], v[56:59]
	v_mfma_f32_16x16x32_bf16 v[92:95], v[132:135], v[190:193], v[92:95]
	v_mfma_f32_16x16x32_bf16 v[88:91], v[156:159], v[190:193], v[88:91]
	v_mfma_f32_16x16x32_bf16 v[84:87], v[132:135], v[198:201], v[84:87]
	v_mfma_f32_16x16x32_bf16 v[80:83], v[156:159], v[198:201], v[80:83]
	v_mfma_f32_16x16x32_bf16 v[76:79], v[132:135], v[206:209], v[76:79]
	v_mfma_f32_16x16x32_bf16 v[72:75], v[156:159], v[206:209], v[72:75]
	v_mfma_f32_16x16x32_bf16 v[64:67], v[132:135], v[214:217], v[64:67]
	v_mfma_f32_16x16x32_bf16 v[56:59], v[156:159], v[214:217], v[56:59]
	s_setprio 0
	s_setprio 1
	v_mfma_f32_16x16x32_bf16 v[28:31], v[160:163], v[186:189], v[28:31]
	v_mfma_f32_16x16x32_bf16 v[24:27], v[168:171], v[186:189], v[24:27]
	v_mfma_f32_16x16x32_bf16 v[20:23], v[160:163], v[194:197], v[20:23]
	v_mfma_f32_16x16x32_bf16 v[16:19], v[168:171], v[194:197], v[16:19]
	v_mfma_f32_16x16x32_bf16 v[12:15], v[160:163], v[202:205], v[12:15]
	v_mfma_f32_16x16x32_bf16 v[8:11], v[168:171], v[202:205], v[8:11]
	v_mfma_f32_16x16x32_bf16 v[4:7], v[160:163], v[210:213], v[4:7]
	v_mfma_f32_16x16x32_bf16 v[0:3], v[168:171], v[210:213], v[0:3]
	v_mfma_f32_16x16x32_bf16 v[28:31], v[164:167], v[190:193], v[28:31]
	v_mfma_f32_16x16x32_bf16 v[24:27], v[182:185], v[190:193], v[24:27]
	v_mfma_f32_16x16x32_bf16 v[20:23], v[164:167], v[198:201], v[20:23]
	v_mfma_f32_16x16x32_bf16 v[16:19], v[182:185], v[198:201], v[16:19]
	v_mfma_f32_16x16x32_bf16 v[12:15], v[164:167], v[206:209], v[12:15]
	v_mfma_f32_16x16x32_bf16 v[8:11], v[182:185], v[206:209], v[8:11]
	v_mfma_f32_16x16x32_bf16 v[4:7], v[164:167], v[214:217], v[4:7]
	v_mfma_f32_16x16x32_bf16 v[0:3], v[182:185], v[214:217], v[0:3]
	s_setprio 0
	s_barrier
	ds_read_b128 v[128:131], v179
	ds_read_b128 v[132:135], v179 offset:1024
	ds_read_b128 v[152:155], v179 offset:2048
	ds_read_b128 v[156:159], v179 offset:3072
	ds_read_b128 v[160:163], v180
	ds_read_b128 v[164:167], v180 offset:1024
	ds_read_b128 v[168:171], v180 offset:2048
	ds_read_b128 v[182:185], v180 offset:3072
	s_add_u32 s24, s24, 0x160000
	s_addc_u32 s25, s25, 0
	s_mov_b32 m0, s30
	v_lshl_add_u64 v[224:225], s[24:25], 0, v[136:137]
	ds_read_b128 v[186:189], v178 offset:32768
	ds_read_b128 v[190:193], v178 offset:33792
	ds_read_b128 v[194:197], v178 offset:34816
	ds_read_b128 v[198:201], v178 offset:35840
	ds_read_b128 v[202:205], v178 offset:36864
	ds_read_b128 v[206:209], v178 offset:37888
	ds_read_b128 v[210:213], v178 offset:38912
	ds_read_b128 v[214:217], v178 offset:39936
	global_load_lds_dwordx4 v[224:225], off
	v_lshl_add_u64 v[224:225], s[24:25], 0, v[140:141]
	s_mov_b32 m0, s31
	s_nop 0
	global_load_lds_dwordx4 v[224:225], off
	s_waitcnt vmcnt(8) lgkmcnt(0)
	s_setprio 1
	s_barrier
	v_mfma_f32_16x16x32_bf16 v[124:127], v[128:131], v[186:189], v[124:127]
	v_mfma_f32_16x16x32_bf16 v[120:123], v[152:155], v[186:189], v[120:123]
	v_mfma_f32_16x16x32_bf16 v[116:119], v[128:131], v[194:197], v[116:119]
	v_mfma_f32_16x16x32_bf16 v[112:115], v[152:155], v[194:197], v[112:115]
	v_mfma_f32_16x16x32_bf16 v[108:111], v[128:131], v[202:205], v[108:111]
	v_mfma_f32_16x16x32_bf16 v[104:107], v[152:155], v[202:205], v[104:107]
	v_mfma_f32_16x16x32_bf16 v[100:103], v[128:131], v[210:213], v[100:103]
	v_mfma_f32_16x16x32_bf16 v[96:99], v[152:155], v[210:213], v[96:99]
	v_mfma_f32_16x16x32_bf16 v[124:127], v[132:135], v[190:193], v[124:127]
	v_mfma_f32_16x16x32_bf16 v[120:123], v[156:159], v[190:193], v[120:123]
	v_mfma_f32_16x16x32_bf16 v[116:119], v[132:135], v[198:201], v[116:119]
	v_mfma_f32_16x16x32_bf16 v[112:115], v[156:159], v[198:201], v[112:115]
	v_mfma_f32_16x16x32_bf16 v[108:111], v[132:135], v[206:209], v[108:111]
	v_mfma_f32_16x16x32_bf16 v[104:107], v[156:159], v[206:209], v[104:107]
	v_mfma_f32_16x16x32_bf16 v[100:103], v[132:135], v[214:217], v[100:103]
	v_mfma_f32_16x16x32_bf16 v[96:99], v[156:159], v[214:217], v[96:99]
	s_setprio 0
	s_setprio 1
	v_mfma_f32_16x16x32_bf16 v[68:71], v[160:163], v[186:189], v[68:71]
	v_mfma_f32_16x16x32_bf16 v[60:63], v[168:171], v[186:189], v[60:63]
	v_mfma_f32_16x16x32_bf16 v[52:55], v[160:163], v[194:197], v[52:55]
	v_mfma_f32_16x16x32_bf16 v[48:51], v[168:171], v[194:197], v[48:51]
	v_mfma_f32_16x16x32_bf16 v[44:47], v[160:163], v[202:205], v[44:47]
	v_mfma_f32_16x16x32_bf16 v[40:43], v[168:171], v[202:205], v[40:43]
	v_mfma_f32_16x16x32_bf16 v[36:39], v[160:163], v[210:213], v[36:39]
	v_mfma_f32_16x16x32_bf16 v[32:35], v[168:171], v[210:213], v[32:35]
	v_mfma_f32_16x16x32_bf16 v[68:71], v[164:167], v[190:193], v[68:71]
	v_mfma_f32_16x16x32_bf16 v[60:63], v[182:185], v[190:193], v[60:63]
	v_mfma_f32_16x16x32_bf16 v[52:55], v[164:167], v[198:201], v[52:55]
	v_mfma_f32_16x16x32_bf16 v[48:51], v[182:185], v[198:201], v[48:51]
	v_mfma_f32_16x16x32_bf16 v[44:47], v[164:167], v[206:209], v[44:47]
	v_mfma_f32_16x16x32_bf16 v[40:43], v[182:185], v[206:209], v[40:43]
	v_mfma_f32_16x16x32_bf16 v[36:39], v[164:167], v[214:217], v[36:39]
	v_mfma_f32_16x16x32_bf16 v[32:35], v[182:185], v[214:217], v[32:35]
	s_setprio 0
	s_barrier
; #define PG8_STAGE(bufoff, gbase, voff) do { _Pragma("unroll") for (int _i = 0; _i < 2; ++_i) \
;         __builtin_amdgcn_global_load_lds((const unsigned*)((const char*)(gbase) + (voff)[_i]), (LAS unsigned*)(lds + (bufoff) + ldsw + _i * 8192), 16, 0, 0); } while (0)
; #define PG8_LDA(dst, b, h) do { _Pragma("unroll") for (int m = 0; m < 4; ++m) _Pragma("unroll") for (int k = 0; k < 2; ++k) dst[m][k] = *(const LAS bf16x8*)(lds + PG8_SA(b, h) + aoff + m * 2048 + k * 1024); } while (0)
; #define PG8_MMA(ai, bj, At, Bt) do { __builtin_amdgcn_s_setprio(1); _Pragma("unroll") for (int m = 0; m < 4; ++m) _Pragma("unroll") for (int n = 0; n < 2; ++n) _Pragma("unroll") for (int k = 0; k < 2; ++k) \
;         acc[ai][bj][m][n] = __builtin_amdgcn_mfma_f32_16x16x32_bf16(Bt[n][k], At[m][k], acc[ai][bj][m][n], 0, 0, 0); __builtin_amdgcn_s_setprio(0); } while (0)
; #define PG8_WAIT_V(n) asm volatile("s_waitcnt vmcnt(" #n ")" ::: "memory")
; #define PG8_WAIT_L(n) asm volatile("s_waitcnt lgkmcnt(" #n ")" ::: "memory")
; #define PG8_BAR __builtin_amdgcn_s_barrier()
; #define PG8_SCHED __builtin_amdgcn_sched_barrier(0)
; template <class Epi, class Sched, bool ALIGN_EPI = false, bool SP2 = false>
; __device__ __forceinline__ void gemm_phase(LAS unsigned char* lds, const Gemm g, const Sched& S, const Epi& E) {
;     ...
;             PG8_LDA(At, 1, 1); PG8_STAGE(PG8_SB(1, 0), b3, voffB); PG8_STAGE(PG8_SB(1, 1), b3 + hstepB, voffB); PG8_STAGE(PG8_SA(1, 0), a3, voffA);
;             PG8_WAIT_V(8); PG8_WAIT_L(0); PG8_BAR; PG8_MMA(1, 0, At, B0); PG8_MMA(1, 1, At, B1); PG8_BAR; PG8_SCHED;
;     ...
;         if constexpr (ALIGN_EPI) { if (wr == 0) PG8_BAR; }
	s_add_i32 s24, s42, s27
	v_lshl_add_u64 v[172:173], v[172:173], 0, s[8:9]
	s_mov_b32 m0, s24
	ds_read_b128 v[186:189], v178 offset:49152
	ds_read_b128 v[190:193], v178 offset:50176
	ds_read_b128 v[194:197], v178 offset:51200
	ds_read_b128 v[198:201], v178 offset:52224
	ds_read_b128 v[202:205], v178 offset:53248
	ds_read_b128 v[206:209], v178 offset:54272
	ds_read_b128 v[210:213], v178 offset:55296
	ds_read_b128 v[214:217], v178 offset:56320
	global_load_lds_dwordx4 v[172:173], off
	s_add_i32 m0, s24, 0x2000
	s_add_u32 s22, s22, 0x160080
	v_lshl_add_u64 v[172:173], v[218:219], 0, s[8:9]
	s_addc_u32 s23, s23, 0
	s_add_i32 s24, s43, s27
	global_load_lds_dwordx4 v[172:173], off
	v_lshl_add_u64 v[172:173], s[22:23], 0, v[138:139]
	s_mov_b32 m0, s24
	s_nop 0
	global_load_lds_dwordx4 v[172:173], off
	v_lshl_add_u64 v[172:173], s[22:23], 0, v[142:143]
	s_add_i32 m0, s24, 0x2000
	s_nop 0
	global_load_lds_dwordx4 v[172:173], off
	v_lshl_add_u64 v[172:173], v[220:221], 0, s[8:9]
	s_mov_b32 m0, s36
	s_nop 0
	global_load_lds_dwordx4 v[172:173], off
	v_lshl_add_u64 v[172:173], v[222:223], 0, s[8:9]
	s_mov_b32 m0, s37
	s_nop 0
	global_load_lds_dwordx4 v[172:173], off
	s_waitcnt vmcnt(8) lgkmcnt(0)
	s_setprio 1
	s_barrier
	v_mfma_f32_16x16x32_bf16 v[92:95], v[128:131], v[186:189], v[92:95]
	v_mfma_f32_16x16x32_bf16 v[88:91], v[152:155], v[186:189], v[88:91]
	v_mfma_f32_16x16x32_bf16 v[84:87], v[128:131], v[194:197], v[84:87]
	v_mfma_f32_16x16x32_bf16 v[80:83], v[152:155], v[194:197], v[80:83]
	v_mfma_f32_16x16x32_bf16 v[76:79], v[128:131], v[202:205], v[76:79]
	v_mfma_f32_16x16x32_bf16 v[72:75], v[152:155], v[202:205], v[72:75]
	v_mfma_f32_16x16x32_bf16 v[64:67], v[128:131], v[210:213], v[64:67]
	v_mfma_f32_16x16x32_bf16 v[56:59], v[152:155], v[210:213], v[56:59]
	v_mfma_f32_16x16x32_bf16 v[92:95], v[132:135], v[190:193], v[92:95]
	v_mfma_f32_16x16x32_bf16 v[88:91], v[156:159], v[190:193], v[88:91]
	v_mfma_f32_16x16x32_bf16 v[84:87], v[132:135], v[198:201], v[84:87]
	v_mfma_f32_16x16x32_bf16 v[80:83], v[156:159], v[198:201], v[80:83]
	v_mfma_f32_16x16x32_bf16 v[76:79], v[132:135], v[206:209], v[76:79]
	v_mfma_f32_16x16x32_bf16 v[72:75], v[156:159], v[206:209], v[72:75]
	v_mfma_f32_16x16x32_bf16 v[64:67], v[132:135], v[214:217], v[64:67]
	v_mfma_f32_16x16x32_bf16 v[56:59], v[156:159], v[214:217], v[56:59]
	s_setprio 0
	s_setprio 1
	v_mfma_f32_16x16x32_bf16 v[28:31], v[160:163], v[186:189], v[28:31]
	v_mfma_f32_16x16x32_bf16 v[24:27], v[168:171], v[186:189], v[24:27]
	v_mfma_f32_16x16x32_bf16 v[20:23], v[160:163], v[194:197], v[20:23]
	v_mfma_f32_16x16x32_bf16 v[16:19], v[168:171], v[194:197], v[16:19]
	v_mfma_f32_16x16x32_bf16 v[12:15], v[160:163], v[202:205], v[12:15]
	v_mfma_f32_16x16x32_bf16 v[8:11], v[168:171], v[202:205], v[8:11]
	v_mfma_f32_16x16x32_bf16 v[4:7], v[160:163], v[210:213], v[4:7]
	v_mfma_f32_16x16x32_bf16 v[0:3], v[168:171], v[210:213], v[0:3]
	v_mfma_f32_16x16x32_bf16 v[28:31], v[164:167], v[190:193], v[28:31]
	v_mfma_f32_16x16x32_bf16 v[24:27], v[182:185], v[190:193], v[24:27]
	v_mfma_f32_16x16x32_bf16 v[20:23], v[164:167], v[198:201], v[20:23]
	v_mfma_f32_16x16x32_bf16 v[16:19], v[182:185], v[198:201], v[16:19]
	v_mfma_f32_16x16x32_bf16 v[12:15], v[164:167], v[206:209], v[12:15]
	v_mfma_f32_16x16x32_bf16 v[8:11], v[182:185], v[206:209], v[8:11]
	v_mfma_f32_16x16x32_bf16 v[4:7], v[164:167], v[214:217], v[4:7]
	v_mfma_f32_16x16x32_bf16 v[0:3], v[182:185], v[214:217], v[0:3]
	s_setprio 0
	s_barrier
	s_add_i32 s49, s49, 2
	s_add_u32 s20, s20, 0x100
	s_addc_u32 s21, s21, 0
	s_add_u32 s47, s47, 0x100
	s_addc_u32 s48, s48, 0
	s_cmpk_gt_u32 s49, 0x55
	s_cbranch_scc0 .LBB0_1138
	s_and_b64 vcc, exec, s[10:11]
	s_cbranch_vccz .LBB0_1141
	s_barrier
